# EpiRes (w_o, P6) epilogue: x-tile loads software-pipelined 2 row-groups ahead, counted vmcnt instead of per-load vmcnt(0)
# speedup vs baseline: 1.0025x; 1.0025x over previous
;     DI void operator()(AccRef acc, const Unit& u, int wr, int wc, int fr, int fq) const {
;     ...
;         for (int ai = 0; ai < 2; ++ai) {
;             const int rb = u.pm * 256 + ai * 128 + wr * 64 + fr;
;             int mb, pos0, kv0; row_info(rb, mb, pos0, kv0);
;             f32x4 gt[2][2], gs[2][2];
; #pragma unroll
;             for (int bj = 0; bj < 2; ++bj)
; #pragma unroll
;                 for (int n = 0; n < 2; ++n) {
;                     const int c = u.pn * 256 + bj * 128 + cl + 4 * n;
;                     gt[bj][n] = *(const f32x4*)(gate + (size_t)mb * 6144 + c);
;                     if (ap) { const f32x4 g = *(const f32x4*)(gn + c), s = *(const f32x4*)(scn + (size_t)mb * 6144 + c); gs[bj][n] = g * (s + 1.f); }
;                 }
; #pragma unroll
;             for (int m = 0; m < 4; ++m) {
;                 const int row = rb + 16 * m;
;                 const float* xi = row < MP ? xin_p + (size_t)row * 1024 : xin_s + (size_t)(row - MP) * 1024;
;                 float s = 0.f;
; #pragma unroll
;                 for (int bj = 0; bj < 2; ++bj) {
;                     const int c = u.pn * 256 + bj * 128 + cl;
;                     float v[8];
; #pragma unroll
;                     for (int n = 0; n < 2; ++n) {
;                         const f32x4 x = *(const f32x4*)(xi + c + 4 * n);
;                         const f32x4 y = x + gt[bj][n] * acc[ai][bj][m][n];
;                         *(f32x4*)(xout + (size_t)row * 1024 + c + 4 * n) = y;
.LBB0_1094:
	v_readlane_b32 s3, v253, 32
	v_mbcnt_lo_u32_b32 v100, -1, 0
	v_mbcnt_hi_u32_b32 v100, -1, v100
	s_mov_b32 s3, s30
	v_and_b32_e32 v202, 15, v100
	v_bfe_u32 v204, v100, 4, 2
	s_mov_b32 s12, s36
	s_lshl_b32 s16, s16, 8
	s_lshl_b32 s3, s3, 6
	s_add_i32 s3, s3, s16
	v_add_u32_e32 v192, s3, v202
	s_lshl_b32 s13, s12, 5
	s_lshl_b32 s3, s2, 8
	v_add_u32_e32 v224, 0xffffc000, v192
	s_add_i32 s13, s13, s3
	v_lshrrev_b32_e32 v101, 6, v224
	v_lshl_add_u32 v188, v204, 3, s13
	v_ashrrev_i32_e32 v100, 11, v192
	v_add_u32_e32 v101, 8, v101
	v_cmp_gt_i32_e32 vcc, s94, v192
	v_mov_b64_e32 v[102:103], s[60:61]
	v_ashrrev_i32_e32 v189, 31, v188
	v_cndmask_b32_e32 v104, v101, v100, vcc
	v_mov_b64_e32 v[100:101], s[8:9]
	v_mad_i64_i32 v[100:101], s[16:17], v104, s75, v[100:101]
	v_mad_i64_i32 v[102:103], s[16:17], v104, s75, v[102:103]
	v_lshlrev_b64 v[190:191], 2, v[188:189]
	v_lshl_add_u64 v[104:105], v[100:101], 0, v[190:191]
	v_lshl_add_u64 v[194:195], s[72:73], 0, v[190:191]
	v_lshl_add_u64 v[168:169], v[102:103], 0, v[190:191]
	global_load_dwordx4 v[108:111], v[104:105], off offset:16
	global_load_dwordx4 v[116:119], v[104:105], off
	global_load_dwordx4 v[148:151], v[194:195], off offset:16
	global_load_dwordx4 v[164:167], v[194:195], off
	global_load_dwordx4 v[160:163], v[168:169], off offset:16
	global_load_dwordx4 v[172:175], v[168:169], off
	global_load_dwordx4 v[100:103], v[104:105], off offset:528
	s_nop 0
	global_load_dwordx4 v[104:107], v[104:105], off offset:512
	s_nop 0
	global_load_dwordx4 v[144:147], v[194:195], off offset:528
	global_load_dwordx4 v[156:159], v[194:195], off offset:512
	global_load_dwordx4 v[152:155], v[168:169], off offset:528
	s_nop 0
	global_load_dwordx4 v[168:171], v[168:169], off offset:512
	s_movk_i32 s3, 0x3fff
	v_cmp_lt_i32_e32 vcc, s3, v192
	s_and_saveexec_b64 s[16:17], vcc
	s_xor_b64 s[16:17], exec, s[16:17]
	v_lshlrev_b64 v[196:197], 12, v[224:225]
	v_mov_b32_e32 v193, v225
	v_lshl_add_u64 v[198:199], s[20:21], 0, v[196:197]
	v_lshlrev_b64 v[196:197], 12, v[192:193]
	s_andn2_saveexec_b64 s[16:17], s[16:17]
	v_ashrrev_i32_e32 v193, 31, v192
	v_lshlrev_b64 v[196:197], 12, v[192:193]
	v_lshl_add_u64 v[198:199], s[42:43], 0, v[196:197]
	s_or_b64 exec, exec, s[16:17]
	s_sub_u32 s82, s20, 0x4000000
	s_subb_u32 s83, s21, 0
	s_cmp_ge_u32 s16, 0x4000
	s_cselect_b32 s82, s82, s42
	s_cselect_b32 s83, s83, s43
	v_lshl_add_u32 v206, v192, 12, v190
	v_lshlrev_b32_e32 v213, 11, v192
	v_lshlrev_b32_e32 v209, 6, v192
	v_mov_b32_e32 v207, v206
	v_lshl_add_u32 v208, v188, 1, v213
	global_load_dwordx4 v[232:235], v206, s[82:83] offset:16
	global_load_dwordx4 v[240:243], v206, s[82:83] offset:528
	global_load_dwordx4 v[228:231], v206, s[82:83]
	global_load_dwordx4 v[236:239], v206, s[82:83] offset:512
	v_add_u32_e32 v206, 0x10000, v206
	global_load_dwordx4 v[248:251], v206, s[82:83] offset:16
	global_load_dwordx4 v[220:223], v206, s[82:83] offset:528
	global_load_dwordx4 v[244:247], v206, s[82:83]
	global_load_dwordx4 v[216:219], v206, s[82:83] offset:512
	v_add_u32_e32 v206, 0x10000, v206
	s_waitcnt vmcnt(8)
	v_pk_add_f32 v[172:173], v[172:173], 1.0 op_sel_hi:[1,0]
	v_pk_add_f32 v[154:155], v[154:155], 1.0 op_sel_hi:[1,0]
	v_pk_mul_f32 v[164:165], v[164:165], v[172:173]
	v_pk_add_f32 v[172:173], v[160:161], 1.0 op_sel_hi:[1,0]
	v_pk_add_f32 v[160:161], v[162:163], 1.0 op_sel_hi:[1,0]
	v_pk_mul_f32 v[162:163], v[148:149], v[172:173]
	v_pk_mul_f32 v[160:161], v[150:151], v[160:161]
	v_pk_add_f32 v[148:149], v[170:171], 1.0 op_sel_hi:[1,0]
	v_pk_add_f32 v[150:151], v[168:169], 1.0 op_sel_hi:[1,0]
	v_pk_mul_f32 v[146:147], v[146:147], v[154:155]
	v_lshl_add_u64 v[154:155], v[198:199], 0, v[190:191]
	v_pk_mul_f32 v[148:149], v[158:159], v[148:149]
	v_pk_mul_f32 v[150:151], v[156:157], v[150:151]
	v_pk_add_f32 v[174:175], v[174:175], 1.0 op_sel_hi:[1,0]
	v_pk_add_f32 v[152:153], v[152:153], 1.0 op_sel_hi:[1,0]
	v_pk_mul_f32 v[166:167], v[166:167], v[174:175]
	v_pk_mul_f32 v[144:145], v[144:145], v[152:153]
	v_lshlrev_b64 v[152:153], 11, v[192:193]
	v_lshl_add_u64 v[152:153], s[64:65], 0, v[152:153]
	v_lshlrev_b32_e32 v202, 2, v202
	v_lshl_add_u32 v202, v204, 6, v202
	v_xor_b32_e32 v203, 64, v202
	s_lshl_b32 s2, s2, 2
	v_xor_b32_e32 v202, 0x80, v202
	s_ashr_i32 s3, s2, 31
	s_ashr_i32 s13, s12, 31
	s_lshl_b64 s[2:3], s[2:3], 2
	s_add_u32 s16, s39, s2
	s_addc_u32 s17, s40, s3
	s_lshl_b64 s[2:3], s[12:13], 2
	s_add_u32 s90, s16, s2
	v_cmp_eq_u32_e32 vcc, 0, v204
	s_addc_u32 s91, s17, s3
	s_waitcnt vmcnt(4)
; DI u32x4 pack8(const float* v) { u32x4 w; w.x = pk2(v[0], v[1]); w.y = pk2(v[2], v[3]); w.z = pk2(v[4], v[5]); w.w = pk2(v[6], v[7]); return w; }
; #define xor16_32(s) xor16_32_l((s), fr + 16 * fq)
;     DI void operator()(AccRef acc, const Unit& u, int wr, int wc, int fr, int fq) const {
;     ...
;             for (int m = 0; m < 4; ++m) {
;                 const int row = rb + 16 * m;
;                 const float* xi = row < MP ? xin_p + (size_t)row * 1024 : xin_s + (size_t)(row - MP) * 1024;
;                 float s = 0.f;
; #pragma unroll
;                 for (int bj = 0; bj < 2; ++bj) {
;                     const int c = u.pn * 256 + bj * 128 + cl;
;                     float v[8];
; #pragma unroll
;                     for (int n = 0; n < 2; ++n) {
;                         const f32x4 x = *(const f32x4*)(xi + c + 4 * n);
;                         const f32x4 y = x + gt[bj][n] * acc[ai][bj][m][n];
;                         *(f32x4*)(xout + (size_t)row * 1024 + c + 4 * n) = y;
; #pragma unroll
;                         for (int j = 0; j < 4; ++j) { s += y[j] * y[j]; v[4 * n + j] = ap ? y[j] * gs[bj][n][j] : 0.f; }
;                     }
;                     if (ap) *(u32x4*)(ap + (size_t)row * 1024 + c) = pack8(v);
;                 }
;                 s = xor16_32(s);
;                 if (fq == 0) ssq[(size_t)row * 16 + u.pn * 4 + wc] = s;
	v_pk_fma_f32 v[140:141], v[140:141], v[116:117], v[228:229]
	v_pk_fma_f32 v[142:143], v[142:143], v[118:119], v[230:231]
	global_store_dwordx4 v207, v[140:143], s[92:93]
	v_mul_f32_e32 v210, v141, v141
	v_fmac_f32_e32 v210, v140, v140
	v_fmac_f32_e32 v210, v142, v142
	v_fmac_f32_e32 v210, v143, v143
	v_pk_mul_f32 v[228:229], v[164:165], v[140:141]
	v_pk_mul_f32 v[230:231], v[166:167], v[142:143]
	v_pk_fma_f32 v[136:137], v[136:137], v[108:109], v[232:233]
	v_pk_fma_f32 v[138:139], v[138:139], v[110:111], v[234:235]
	global_store_dwordx4 v207, v[136:139], s[92:93] offset:16
	v_fmac_f32_e32 v210, v136, v136
	v_fmac_f32_e32 v210, v137, v137
	v_fmac_f32_e32 v210, v138, v138
	v_fmac_f32_e32 v210, v139, v139
	v_pk_mul_f32 v[232:233], v[162:163], v[136:137]
	v_pk_mul_f32 v[234:235], v[160:161], v[138:139]
	v_cvt_pk_bf16_f32 v228, v228, v229
	v_cvt_pk_bf16_f32 v229, v230, v231
	v_cvt_pk_bf16_f32 v230, v232, v233
	v_cvt_pk_bf16_f32 v231, v234, v235
	global_store_dwordx4 v208, v[228:231], s[64:65]
	v_pk_fma_f32 v[132:133], v[132:133], v[104:105], v[236:237]
	v_pk_fma_f32 v[134:135], v[134:135], v[106:107], v[238:239]
	global_store_dwordx4 v207, v[132:135], s[92:93] offset:512
	v_fmac_f32_e32 v210, v132, v132
	v_fmac_f32_e32 v210, v133, v133
	v_fmac_f32_e32 v210, v134, v134
	v_fmac_f32_e32 v210, v135, v135
	v_pk_mul_f32 v[236:237], v[150:151], v[132:133]
	v_pk_mul_f32 v[238:239], v[148:149], v[134:135]
	v_pk_fma_f32 v[128:129], v[128:129], v[100:101], v[240:241]
	v_pk_fma_f32 v[130:131], v[130:131], v[102:103], v[242:243]
	global_store_dwordx4 v207, v[128:131], s[92:93] offset:528
	v_fmac_f32_e32 v210, v128, v128
	v_fmac_f32_e32 v210, v129, v129
	v_fmac_f32_e32 v210, v130, v130
	v_fmac_f32_e32 v210, v131, v131
	v_pk_mul_f32 v[240:241], v[144:145], v[128:129]
	v_pk_mul_f32 v[242:243], v[146:147], v[130:131]
	v_cvt_pk_bf16_f32 v236, v236, v237
	v_cvt_pk_bf16_f32 v237, v238, v239
	v_cvt_pk_bf16_f32 v238, v240, v241
	v_cvt_pk_bf16_f32 v239, v242, v243
	global_store_dwordx4 v208, v[236:239], s[64:65] offset:256
	ds_bpermute_b32 v211, v203, v210
	v_add_u32_e32 v207, 0x10000, v207
	global_load_dwordx4 v[232:235], v206, s[82:83] offset:16
	global_load_dwordx4 v[240:243], v206, s[82:83] offset:528
	global_load_dwordx4 v[228:231], v206, s[82:83]
	global_load_dwordx4 v[236:239], v206, s[82:83] offset:512
	s_waitcnt lgkmcnt(0)
	v_add_f32_e32 v211, v210, v211
	ds_bpermute_b32 v212, v202, v211
	v_add_u32_e32 v208, 0x8000, v208
	s_waitcnt lgkmcnt(0)
	v_add_f32_e32 v211, v211, v212
	s_mov_b64 exec, 0xffff
	global_store_dword v209, v211, s[90:91]
	s_mov_b64 exec, -1
	v_add_u32_e32 v209, 0x400, v209
	s_waitcnt vmcnt(11)
	v_pk_fma_f32 v[124:125], v[124:125], v[116:117], v[244:245]
	v_pk_fma_f32 v[126:127], v[126:127], v[118:119], v[246:247]
	global_store_dwordx4 v207, v[124:127], s[92:93]
	v_mul_f32_e32 v210, v125, v125
	v_fmac_f32_e32 v210, v124, v124
	v_fmac_f32_e32 v210, v126, v126
	v_fmac_f32_e32 v210, v127, v127
	v_pk_mul_f32 v[244:245], v[164:165], v[124:125]
	v_pk_mul_f32 v[246:247], v[166:167], v[126:127]
	v_pk_fma_f32 v[120:121], v[120:121], v[108:109], v[248:249]
	v_pk_fma_f32 v[122:123], v[122:123], v[110:111], v[250:251]
	global_store_dwordx4 v207, v[120:123], s[92:93] offset:16
	v_fmac_f32_e32 v210, v120, v120
	v_fmac_f32_e32 v210, v121, v121
	v_fmac_f32_e32 v210, v122, v122
	v_fmac_f32_e32 v210, v123, v123
	v_pk_mul_f32 v[248:249], v[162:163], v[120:121]
	v_pk_mul_f32 v[250:251], v[160:161], v[122:123]
	v_cvt_pk_bf16_f32 v244, v244, v245
	v_cvt_pk_bf16_f32 v245, v246, v247
	v_cvt_pk_bf16_f32 v246, v248, v249
	v_cvt_pk_bf16_f32 v247, v250, v251
	global_store_dwordx4 v208, v[244:247], s[64:65]
	v_pk_fma_f32 v[112:113], v[112:113], v[104:105], v[216:217]
	v_pk_fma_f32 v[114:115], v[114:115], v[106:107], v[218:219]
	global_store_dwordx4 v207, v[112:115], s[92:93] offset:512
	v_fmac_f32_e32 v210, v112, v112
	v_fmac_f32_e32 v210, v113, v113
	v_fmac_f32_e32 v210, v114, v114
	v_fmac_f32_e32 v210, v115, v115
	v_pk_mul_f32 v[216:217], v[150:151], v[112:113]
	v_pk_mul_f32 v[218:219], v[148:149], v[114:115]
	v_pk_fma_f32 v[96:97], v[96:97], v[100:101], v[220:221]
	v_pk_fma_f32 v[98:99], v[98:99], v[102:103], v[222:223]
	global_store_dwordx4 v207, v[96:99], s[92:93] offset:528
	v_fmac_f32_e32 v210, v96, v96
	v_fmac_f32_e32 v210, v97, v97
	v_fmac_f32_e32 v210, v98, v98
	v_fmac_f32_e32 v210, v99, v99
	v_pk_mul_f32 v[220:221], v[144:145], v[96:97]
	v_pk_mul_f32 v[222:223], v[146:147], v[98:99]
	v_cvt_pk_bf16_f32 v216, v216, v217
	v_cvt_pk_bf16_f32 v217, v218, v219
	v_cvt_pk_bf16_f32 v218, v220, v221
	v_cvt_pk_bf16_f32 v219, v222, v223
	global_store_dwordx4 v208, v[216:219], s[64:65] offset:256
	ds_bpermute_b32 v211, v203, v210
	v_add_u32_e32 v207, 0x10000, v207
	v_add_u32_e32 v206, 0x10000, v206
	global_load_dwordx4 v[248:251], v206, s[82:83] offset:16
	global_load_dwordx4 v[220:223], v206, s[82:83] offset:528
	global_load_dwordx4 v[244:247], v206, s[82:83]
	global_load_dwordx4 v[216:219], v206, s[82:83] offset:512
	s_waitcnt lgkmcnt(0)
	v_add_f32_e32 v211, v210, v211
	ds_bpermute_b32 v212, v202, v211
	v_add_u32_e32 v208, 0x8000, v208
	s_waitcnt lgkmcnt(0)
	v_add_f32_e32 v211, v211, v212
	s_mov_b64 exec, 0xffff
	global_store_dword v209, v211, s[90:91]
	s_mov_b64 exec, -1
	v_add_u32_e32 v209, 0x400, v209
	s_waitcnt vmcnt(12)
; DI u32x4 pack8(const float* v) { u32x4 w; w.x = pk2(v[0], v[1]); w.y = pk2(v[2], v[3]); w.z = pk2(v[4], v[5]); w.w = pk2(v[6], v[7]); return w; }
; #define xor16_32(s) xor16_32_l((s), fr + 16 * fq)
;     DI void operator()(AccRef acc, const Unit& u, int wr, int wc, int fr, int fq) const {
;     ...
;             for (int m = 0; m < 4; ++m) {
;                 const int row = rb + 16 * m;
;                 const float* xi = row < MP ? xin_p + (size_t)row * 1024 : xin_s + (size_t)(row - MP) * 1024;
;                 float s = 0.f;
; #pragma unroll
;                 for (int bj = 0; bj < 2; ++bj) {
;                     const int c = u.pn * 256 + bj * 128 + cl;
;                     float v[8];
; #pragma unroll
;                     for (int n = 0; n < 2; ++n) {
;                         const f32x4 x = *(const f32x4*)(xi + c + 4 * n);
;                         const f32x4 y = x + gt[bj][n] * acc[ai][bj][m][n];
;                         *(f32x4*)(xout + (size_t)row * 1024 + c + 4 * n) = y;
; #pragma unroll
;                         for (int j = 0; j < 4; ++j) { s += y[j] * y[j]; v[4 * n + j] = ap ? y[j] * gs[bj][n][j] : 0.f; }
;                     }
;                     if (ap) *(u32x4*)(ap + (size_t)row * 1024 + c) = pack8(v);
;                 }
;                 s = xor16_32(s);
;                 if (fq == 0) ssq[(size_t)row * 16 + u.pn * 4 + wc] = s;
	v_pk_fma_f32 v[92:93], v[92:93], v[116:117], v[228:229]
	v_pk_fma_f32 v[94:95], v[94:95], v[118:119], v[230:231]
	global_store_dwordx4 v207, v[92:95], s[92:93]
	v_mul_f32_e32 v210, v93, v93
	v_fmac_f32_e32 v210, v92, v92
	v_fmac_f32_e32 v210, v94, v94
	v_fmac_f32_e32 v210, v95, v95
	v_pk_mul_f32 v[228:229], v[164:165], v[92:93]
	v_pk_mul_f32 v[230:231], v[166:167], v[94:95]
	v_pk_fma_f32 v[88:89], v[88:89], v[108:109], v[232:233]
	v_pk_fma_f32 v[90:91], v[90:91], v[110:111], v[234:235]
	global_store_dwordx4 v207, v[88:91], s[92:93] offset:16
	v_fmac_f32_e32 v210, v88, v88
	v_fmac_f32_e32 v210, v89, v89
	v_fmac_f32_e32 v210, v90, v90
	v_fmac_f32_e32 v210, v91, v91
	v_pk_mul_f32 v[232:233], v[162:163], v[88:89]
	v_pk_mul_f32 v[234:235], v[160:161], v[90:91]
	v_cvt_pk_bf16_f32 v228, v228, v229
	v_cvt_pk_bf16_f32 v229, v230, v231
	v_cvt_pk_bf16_f32 v230, v232, v233
	v_cvt_pk_bf16_f32 v231, v234, v235
	global_store_dwordx4 v208, v[228:231], s[64:65]
	v_pk_fma_f32 v[84:85], v[84:85], v[104:105], v[236:237]
	v_pk_fma_f32 v[86:87], v[86:87], v[106:107], v[238:239]
	global_store_dwordx4 v207, v[84:87], s[92:93] offset:512
	v_fmac_f32_e32 v210, v84, v84
	v_fmac_f32_e32 v210, v85, v85
	v_fmac_f32_e32 v210, v86, v86
	v_fmac_f32_e32 v210, v87, v87
	v_pk_mul_f32 v[236:237], v[150:151], v[84:85]
	v_pk_mul_f32 v[238:239], v[148:149], v[86:87]
	v_pk_fma_f32 v[80:81], v[80:81], v[100:101], v[240:241]
	v_pk_fma_f32 v[82:83], v[82:83], v[102:103], v[242:243]
	global_store_dwordx4 v207, v[80:83], s[92:93] offset:528
	v_fmac_f32_e32 v210, v80, v80
	v_fmac_f32_e32 v210, v81, v81
	v_fmac_f32_e32 v210, v82, v82
	v_fmac_f32_e32 v210, v83, v83
	v_pk_mul_f32 v[240:241], v[144:145], v[80:81]
	v_pk_mul_f32 v[242:243], v[146:147], v[82:83]
	v_cvt_pk_bf16_f32 v236, v236, v237
	v_cvt_pk_bf16_f32 v237, v238, v239
	v_cvt_pk_bf16_f32 v238, v240, v241
	v_cvt_pk_bf16_f32 v239, v242, v243
	global_store_dwordx4 v208, v[236:239], s[64:65] offset:256
	ds_bpermute_b32 v211, v203, v210
	v_add_u32_e32 v207, 0x10000, v207
	v_add_u32_e32 v206, 0x50000, v206
	global_load_dwordx4 v[232:235], v206, s[82:83] offset:16
	global_load_dwordx4 v[240:243], v206, s[82:83] offset:528
	global_load_dwordx4 v[228:231], v206, s[82:83]
	global_load_dwordx4 v[236:239], v206, s[82:83] offset:512
	s_waitcnt lgkmcnt(0)
	v_add_f32_e32 v211, v210, v211
	ds_bpermute_b32 v212, v202, v211
	v_add_u32_e32 v208, 0x8000, v208
	s_waitcnt lgkmcnt(0)
	v_add_f32_e32 v211, v211, v212
	s_mov_b64 exec, 0xffff
	global_store_dword v209, v211, s[90:91]
	s_mov_b64 exec, -1
	v_add_u32_e32 v209, 0x400, v209
	s_waitcnt vmcnt(12)
	v_pk_fma_f32 v[76:77], v[76:77], v[116:117], v[244:245]
	v_pk_fma_f32 v[78:79], v[78:79], v[118:119], v[246:247]
	global_store_dwordx4 v207, v[76:79], s[92:93]
	v_mul_f32_e32 v210, v77, v77
	v_fmac_f32_e32 v210, v76, v76
	v_fmac_f32_e32 v210, v78, v78
	v_fmac_f32_e32 v210, v79, v79
	v_pk_mul_f32 v[244:245], v[164:165], v[76:77]
	v_pk_mul_f32 v[246:247], v[166:167], v[78:79]
	v_pk_fma_f32 v[72:73], v[72:73], v[108:109], v[248:249]
	v_pk_fma_f32 v[74:75], v[74:75], v[110:111], v[250:251]
	global_store_dwordx4 v207, v[72:75], s[92:93] offset:16
	v_fmac_f32_e32 v210, v72, v72
	v_fmac_f32_e32 v210, v73, v73
	v_fmac_f32_e32 v210, v74, v74
	v_fmac_f32_e32 v210, v75, v75
	v_pk_mul_f32 v[248:249], v[162:163], v[72:73]
	v_pk_mul_f32 v[250:251], v[160:161], v[74:75]
	v_cvt_pk_bf16_f32 v244, v244, v245
	v_cvt_pk_bf16_f32 v245, v246, v247
	v_cvt_pk_bf16_f32 v246, v248, v249
	v_cvt_pk_bf16_f32 v247, v250, v251
	global_store_dwordx4 v208, v[244:247], s[64:65]
	v_pk_fma_f32 v[68:69], v[68:69], v[104:105], v[216:217]
	v_pk_fma_f32 v[70:71], v[70:71], v[106:107], v[218:219]
	global_store_dwordx4 v207, v[68:71], s[92:93] offset:512
	v_fmac_f32_e32 v210, v68, v68
	v_fmac_f32_e32 v210, v69, v69
	v_fmac_f32_e32 v210, v70, v70
	v_fmac_f32_e32 v210, v71, v71
	v_pk_mul_f32 v[216:217], v[150:151], v[68:69]
	v_pk_mul_f32 v[218:219], v[148:149], v[70:71]
	v_pk_fma_f32 v[64:65], v[64:65], v[100:101], v[220:221]
	v_pk_fma_f32 v[66:67], v[66:67], v[102:103], v[222:223]
	global_store_dwordx4 v207, v[64:67], s[92:93] offset:528
	v_fmac_f32_e32 v210, v64, v64
	v_fmac_f32_e32 v210, v65, v65
	v_fmac_f32_e32 v210, v66, v66
	v_fmac_f32_e32 v210, v67, v67
	v_pk_mul_f32 v[220:221], v[144:145], v[64:65]
	v_pk_mul_f32 v[222:223], v[146:147], v[66:67]
	v_cvt_pk_bf16_f32 v216, v216, v217
	v_cvt_pk_bf16_f32 v217, v218, v219
	v_cvt_pk_bf16_f32 v218, v220, v221
	v_cvt_pk_bf16_f32 v219, v222, v223
	global_store_dwordx4 v208, v[216:219], s[64:65] offset:256
	ds_bpermute_b32 v211, v203, v210
	v_add_u32_e32 v207, 0x50000, v207
	v_add_u32_e32 v206, 0x10000, v206
	global_load_dwordx4 v[248:251], v206, s[82:83] offset:16
	global_load_dwordx4 v[220:223], v206, s[82:83] offset:528
	global_load_dwordx4 v[244:247], v206, s[82:83]
	global_load_dwordx4 v[216:219], v206, s[82:83] offset:512
	s_waitcnt lgkmcnt(0)
	v_add_f32_e32 v211, v210, v211
	ds_bpermute_b32 v212, v202, v211
	v_add_u32_e32 v208, 0x28000, v208
	s_waitcnt lgkmcnt(0)
	v_add_f32_e32 v211, v211, v212
	s_mov_b64 exec, 0xffff
	global_store_dword v209, v211, s[90:91]
	s_mov_b64 exec, -1
	v_add_u32_e32 v209, 0x1400, v209
	v_add_u32_e32 v224, 0xffffc080, v192
	v_add_u32_e32 v112, 0x80, v192
	s_waitcnt lgkmcnt(0)
; DI u32x4 pack8(const float* v) { u32x4 w; w.x = pk2(v[0], v[1]); w.y = pk2(v[2], v[3]); w.z = pk2(v[4], v[5]); w.w = pk2(v[6], v[7]); return w; }
; #define xor16_32(s) xor16_32_l((s), fr + 16 * fq)
;     DI void operator()(AccRef acc, const Unit& u, int wr, int wc, int fr, int fq) const {
;     ...
;         for (int ai = 0; ai < 2; ++ai) {
;             const int rb = u.pm * 256 + ai * 128 + wr * 64 + fr;
;             int mb, pos0, kv0; row_info(rb, mb, pos0, kv0);
;             f32x4 gt[2][2], gs[2][2];
; #pragma unroll
;             for (int bj = 0; bj < 2; ++bj)
; #pragma unroll
;                 for (int n = 0; n < 2; ++n) {
;                     const int c = u.pn * 256 + bj * 128 + cl + 4 * n;
;                     gt[bj][n] = *(const f32x4*)(gate + (size_t)mb * 6144 + c);
;                     if (ap) { const f32x4 g = *(const f32x4*)(gn + c), s = *(const f32x4*)(scn + (size_t)mb * 6144 + c); gs[bj][n] = g * (s + 1.f); }
;                 }
; #pragma unroll
;             for (int m = 0; m < 4; ++m) {
;                 const int row = rb + 16 * m;
;                 const float* xi = row < MP ? xin_p + (size_t)row * 1024 : xin_s + (size_t)(row - MP) * 1024;
;                 float s = 0.f;
; #pragma unroll
;                 for (int bj = 0; bj < 2; ++bj) {
;                     const int c = u.pn * 256 + bj * 128 + cl;
;                     float v[8];
; #pragma unroll
;                     for (int n = 0; n < 2; ++n) {
;                         const f32x4 x = *(const f32x4*)(xi + c + 4 * n);
;                         const f32x4 y = x + gt[bj][n] * acc[ai][bj][m][n];
;                         *(f32x4*)(xout + (size_t)row * 1024 + c + 4 * n) = y;
; #pragma unroll
;                         for (int j = 0; j < 4; ++j) { s += y[j] * y[j]; v[4 * n + j] = ap ? y[j] * gs[bj][n][j] : 0.f; }
;                     }
;                     if (ap) *(u32x4*)(ap + (size_t)row * 1024 + c) = pack8(v);
;                 }
;                 s = xor16_32(s);
;                 if (fq == 0) ssq[(size_t)row * 16 + u.pn * 4 + wc] = s;
	v_lshrrev_b32_e32 v65, 6, v224
	v_ashrrev_i32_e32 v64, 11, v112
	v_add_u32_e32 v65, 8, v65
	v_cmp_gt_i32_e64 s[2:3], s94, v112
	v_mov_b64_e32 v[66:67], s[60:61]
	s_nop 0
	v_cndmask_b32_e64 v68, v65, v64, s[2:3]
	v_mov_b64_e32 v[64:65], s[8:9]
	v_mad_i64_i32 v[64:65], s[2:3], v68, s75, v[64:65]
	v_mad_i64_i32 v[66:67], s[2:3], v68, s75, v[66:67]
	v_lshl_add_u64 v[68:69], v[64:65], 0, v[190:191]
	v_lshl_add_u64 v[104:105], v[66:67], 0, v[190:191]
	global_load_dwordx4 v[72:75], v[68:69], off offset:16
	global_load_dwordx4 v[76:79], v[68:69], off
	global_load_dwordx4 v[84:87], v[194:195], off offset:16
	global_load_dwordx4 v[100:103], v[194:195], off
	global_load_dwordx4 v[96:99], v[104:105], off offset:16
	global_load_dwordx4 v[108:111], v[104:105], off
	global_load_dwordx4 v[64:67], v[68:69], off offset:528
	s_nop 0
	global_load_dwordx4 v[68:71], v[68:69], off offset:512
	s_nop 0
	global_load_dwordx4 v[80:83], v[194:195], off offset:528
	global_load_dwordx4 v[92:95], v[194:195], off offset:512
	global_load_dwordx4 v[88:91], v[104:105], off offset:528
	s_nop 0
	global_load_dwordx4 v[104:107], v[104:105], off offset:512
	s_movk_i32 s2, 0x3fff
	v_cmp_lt_i32_e64 s[2:3], s2, v112
	s_and_saveexec_b64 s[12:13], s[2:3]
	s_xor_b64 s[2:3], exec, s[12:13]
	v_lshlrev_b64 v[114:115], 12, v[224:225]
	v_mov_b32_e32 v113, v225
	v_lshl_add_u64 v[116:117], s[20:21], 0, v[114:115]
	v_lshlrev_b64 v[114:115], 12, v[112:113]
	s_andn2_saveexec_b64 s[2:3], s[2:3]
	v_ashrrev_i32_e32 v113, 31, v112
	v_lshlrev_b64 v[114:115], 12, v[112:113]
	v_lshl_add_u64 v[116:117], s[42:43], 0, v[114:115]
	s_or_b64 exec, exec, s[2:3]
	s_waitcnt vmcnt(6)
	v_pk_add_f32 v[108:109], v[108:109], 1.0 op_sel_hi:[1,0]
	s_waitcnt vmcnt(1)
	v_pk_add_f32 v[90:91], v[90:91], 1.0 op_sel_hi:[1,0]
	v_pk_mul_f32 v[100:101], v[100:101], v[108:109]
	v_pk_add_f32 v[108:109], v[96:97], 1.0 op_sel_hi:[1,0]
	v_pk_add_f32 v[96:97], v[98:99], 1.0 op_sel_hi:[1,0]
	v_pk_mul_f32 v[98:99], v[84:85], v[108:109]
	v_pk_mul_f32 v[96:97], v[86:87], v[96:97]
	s_waitcnt vmcnt(0)
	v_pk_add_f32 v[84:85], v[106:107], 1.0 op_sel_hi:[1,0]
	v_pk_add_f32 v[86:87], v[104:105], 1.0 op_sel_hi:[1,0]
	v_pk_mul_f32 v[82:83], v[82:83], v[90:91]
	v_lshl_add_u64 v[90:91], v[116:117], 0, v[190:191]
	v_pk_mul_f32 v[84:85], v[94:95], v[84:85]
	v_pk_mul_f32 v[86:87], v[92:93], v[86:87]
	v_pk_add_f32 v[110:111], v[110:111], 1.0 op_sel_hi:[1,0]
	v_pk_add_f32 v[88:89], v[88:89], 1.0 op_sel_hi:[1,0]
	v_pk_mul_f32 v[102:103], v[102:103], v[110:111]
	v_pk_mul_f32 v[80:81], v[80:81], v[88:89]
	v_lshlrev_b64 v[88:89], 11, v[112:113]
	v_lshl_add_u64 v[88:89], s[64:65], 0, v[88:89]
	v_pk_fma_f32 v[60:61], v[60:61], v[76:77], v[228:229]
	v_pk_fma_f32 v[62:63], v[62:63], v[78:79], v[230:231]
	global_store_dwordx4 v207, v[60:63], s[92:93]
	v_mul_f32_e32 v210, v61, v61
	v_fmac_f32_e32 v210, v60, v60
	v_fmac_f32_e32 v210, v62, v62
	v_fmac_f32_e32 v210, v63, v63
	v_pk_mul_f32 v[228:229], v[100:101], v[60:61]
	v_pk_mul_f32 v[230:231], v[102:103], v[62:63]
	v_pk_fma_f32 v[56:57], v[56:57], v[72:73], v[232:233]
	v_pk_fma_f32 v[58:59], v[58:59], v[74:75], v[234:235]
	global_store_dwordx4 v207, v[56:59], s[92:93] offset:16
	v_fmac_f32_e32 v210, v56, v56
	v_fmac_f32_e32 v210, v57, v57
	v_fmac_f32_e32 v210, v58, v58
	v_fmac_f32_e32 v210, v59, v59
	v_pk_mul_f32 v[232:233], v[98:99], v[56:57]
	v_pk_mul_f32 v[234:235], v[96:97], v[58:59]
	v_cvt_pk_bf16_f32 v228, v228, v229
	v_cvt_pk_bf16_f32 v229, v230, v231
	v_cvt_pk_bf16_f32 v230, v232, v233
	v_cvt_pk_bf16_f32 v231, v234, v235
	global_store_dwordx4 v208, v[228:231], s[64:65]
	v_pk_fma_f32 v[52:53], v[52:53], v[68:69], v[236:237]
	v_pk_fma_f32 v[54:55], v[54:55], v[70:71], v[238:239]
	global_store_dwordx4 v207, v[52:55], s[92:93] offset:512
	v_fmac_f32_e32 v210, v52, v52
	v_fmac_f32_e32 v210, v53, v53
	v_fmac_f32_e32 v210, v54, v54
	v_fmac_f32_e32 v210, v55, v55
	v_pk_mul_f32 v[236:237], v[86:87], v[52:53]
	v_pk_mul_f32 v[238:239], v[84:85], v[54:55]
	v_pk_fma_f32 v[48:49], v[48:49], v[64:65], v[240:241]
	v_pk_fma_f32 v[50:51], v[50:51], v[66:67], v[242:243]
	global_store_dwordx4 v207, v[48:51], s[92:93] offset:528
	v_fmac_f32_e32 v210, v48, v48
	v_fmac_f32_e32 v210, v49, v49
	v_fmac_f32_e32 v210, v50, v50
	v_fmac_f32_e32 v210, v51, v51
	v_pk_mul_f32 v[240:241], v[80:81], v[48:49]
	v_pk_mul_f32 v[242:243], v[82:83], v[50:51]
	v_cvt_pk_bf16_f32 v236, v236, v237
	v_cvt_pk_bf16_f32 v237, v238, v239
	v_cvt_pk_bf16_f32 v238, v240, v241
	v_cvt_pk_bf16_f32 v239, v242, v243
	global_store_dwordx4 v208, v[236:239], s[64:65] offset:256
	ds_bpermute_b32 v211, v203, v210
	v_add_u32_e32 v207, 0x10000, v207
	v_add_u32_e32 v206, 0x10000, v206
	global_load_dwordx4 v[232:235], v206, s[82:83] offset:16
	global_load_dwordx4 v[240:243], v206, s[82:83] offset:528
	global_load_dwordx4 v[228:231], v206, s[82:83]
	global_load_dwordx4 v[236:239], v206, s[82:83] offset:512
	s_waitcnt lgkmcnt(0)
	v_add_f32_e32 v211, v210, v211
	ds_bpermute_b32 v212, v202, v211
	v_add_u32_e32 v208, 0x8000, v208
	s_waitcnt lgkmcnt(0)
; DI u32x4 pack8(const float* v) { u32x4 w; w.x = pk2(v[0], v[1]); w.y = pk2(v[2], v[3]); w.z = pk2(v[4], v[5]); w.w = pk2(v[6], v[7]); return w; }
; #define xor16_32(s) xor16_32_l((s), fr + 16 * fq)
;     DI void operator()(AccRef acc, const Unit& u, int wr, int wc, int fr, int fq) const {
;     ...
;             for (int m = 0; m < 4; ++m) {
;                 const int row = rb + 16 * m;
;                 const float* xi = row < MP ? xin_p + (size_t)row * 1024 : xin_s + (size_t)(row - MP) * 1024;
;                 float s = 0.f;
; #pragma unroll
;                 for (int bj = 0; bj < 2; ++bj) {
;                     const int c = u.pn * 256 + bj * 128 + cl;
;                     float v[8];
; #pragma unroll
;                     for (int n = 0; n < 2; ++n) {
;                         const f32x4 x = *(const f32x4*)(xi + c + 4 * n);
;                         const f32x4 y = x + gt[bj][n] * acc[ai][bj][m][n];
;                         *(f32x4*)(xout + (size_t)row * 1024 + c + 4 * n) = y;
; #pragma unroll
;                         for (int j = 0; j < 4; ++j) { s += y[j] * y[j]; v[4 * n + j] = ap ? y[j] * gs[bj][n][j] : 0.f; }
;                     }
;                     if (ap) *(u32x4*)(ap + (size_t)row * 1024 + c) = pack8(v);
;                 }
;                 s = xor16_32(s);
;                 if (fq == 0) ssq[(size_t)row * 16 + u.pn * 4 + wc] = s;
	v_add_f32_e32 v211, v211, v212
	s_mov_b64 exec, 0xffff
	global_store_dword v209, v211, s[90:91]
	s_mov_b64 exec, -1
	v_add_u32_e32 v209, 0x400, v209
	v_pk_fma_f32 v[44:45], v[44:45], v[76:77], v[244:245]
	v_pk_fma_f32 v[46:47], v[46:47], v[78:79], v[246:247]
	global_store_dwordx4 v207, v[44:47], s[92:93]
	v_mul_f32_e32 v210, v45, v45
	v_fmac_f32_e32 v210, v44, v44
	v_fmac_f32_e32 v210, v46, v46
	v_fmac_f32_e32 v210, v47, v47
	v_pk_mul_f32 v[244:245], v[100:101], v[44:45]
	v_pk_mul_f32 v[246:247], v[102:103], v[46:47]
	v_pk_fma_f32 v[40:41], v[40:41], v[72:73], v[248:249]
	v_pk_fma_f32 v[42:43], v[42:43], v[74:75], v[250:251]
	global_store_dwordx4 v207, v[40:43], s[92:93] offset:16
	v_fmac_f32_e32 v210, v40, v40
	v_fmac_f32_e32 v210, v41, v41
	v_fmac_f32_e32 v210, v42, v42
	v_fmac_f32_e32 v210, v43, v43
	v_pk_mul_f32 v[248:249], v[98:99], v[40:41]
	v_pk_mul_f32 v[250:251], v[96:97], v[42:43]
	v_cvt_pk_bf16_f32 v244, v244, v245
	v_cvt_pk_bf16_f32 v245, v246, v247
	v_cvt_pk_bf16_f32 v246, v248, v249
	v_cvt_pk_bf16_f32 v247, v250, v251
	global_store_dwordx4 v208, v[244:247], s[64:65]
	v_pk_fma_f32 v[36:37], v[36:37], v[68:69], v[216:217]
	v_pk_fma_f32 v[38:39], v[38:39], v[70:71], v[218:219]
	global_store_dwordx4 v207, v[36:39], s[92:93] offset:512
	v_fmac_f32_e32 v210, v36, v36
	v_fmac_f32_e32 v210, v37, v37
	v_fmac_f32_e32 v210, v38, v38
	v_fmac_f32_e32 v210, v39, v39
	v_pk_mul_f32 v[216:217], v[86:87], v[36:37]
	v_pk_mul_f32 v[218:219], v[84:85], v[38:39]
	v_pk_fma_f32 v[32:33], v[32:33], v[64:65], v[220:221]
	v_pk_fma_f32 v[34:35], v[34:35], v[66:67], v[222:223]
	global_store_dwordx4 v207, v[32:35], s[92:93] offset:528
	v_fmac_f32_e32 v210, v32, v32
	v_fmac_f32_e32 v210, v33, v33
	v_fmac_f32_e32 v210, v34, v34
	v_fmac_f32_e32 v210, v35, v35
	v_pk_mul_f32 v[220:221], v[80:81], v[32:33]
	v_pk_mul_f32 v[222:223], v[82:83], v[34:35]
	v_cvt_pk_bf16_f32 v216, v216, v217
	v_cvt_pk_bf16_f32 v217, v218, v219
	v_cvt_pk_bf16_f32 v218, v220, v221
	v_cvt_pk_bf16_f32 v219, v222, v223
	global_store_dwordx4 v208, v[216:219], s[64:65] offset:256
	ds_bpermute_b32 v211, v203, v210
	v_add_u32_e32 v207, 0x10000, v207
	v_add_u32_e32 v206, 0x10000, v206
	global_load_dwordx4 v[248:251], v206, s[82:83] offset:16
	global_load_dwordx4 v[220:223], v206, s[82:83] offset:528
	global_load_dwordx4 v[244:247], v206, s[82:83]
	global_load_dwordx4 v[216:219], v206, s[82:83] offset:512
	s_waitcnt lgkmcnt(0)
	v_add_f32_e32 v211, v210, v211
	ds_bpermute_b32 v212, v202, v211
	v_add_u32_e32 v208, 0x8000, v208
	s_waitcnt lgkmcnt(0)
	v_add_f32_e32 v211, v211, v212
	s_mov_b64 exec, 0xffff
	global_store_dword v209, v211, s[90:91]
	s_mov_b64 exec, -1
	v_add_u32_e32 v209, 0x400, v209
	s_waitcnt vmcnt(12)
; DI u32x4 pack8(const float* v) { u32x4 w; w.x = pk2(v[0], v[1]); w.y = pk2(v[2], v[3]); w.z = pk2(v[4], v[5]); w.w = pk2(v[6], v[7]); return w; }
; #define xor16_32(s) xor16_32_l((s), fr + 16 * fq)
;     DI void operator()(AccRef acc, const Unit& u, int wr, int wc, int fr, int fq) const {
;     ...
;             for (int m = 0; m < 4; ++m) {
;                 const int row = rb + 16 * m;
;                 const float* xi = row < MP ? xin_p + (size_t)row * 1024 : xin_s + (size_t)(row - MP) * 1024;
;                 float s = 0.f;
; #pragma unroll
;                 for (int bj = 0; bj < 2; ++bj) {
;                     const int c = u.pn * 256 + bj * 128 + cl;
;                     float v[8];
; #pragma unroll
;                     for (int n = 0; n < 2; ++n) {
;                         const f32x4 x = *(const f32x4*)(xi + c + 4 * n);
;                         const f32x4 y = x + gt[bj][n] * acc[ai][bj][m][n];
;                         *(f32x4*)(xout + (size_t)row * 1024 + c + 4 * n) = y;
; #pragma unroll
;                         for (int j = 0; j < 4; ++j) { s += y[j] * y[j]; v[4 * n + j] = ap ? y[j] * gs[bj][n][j] : 0.f; }
;                     }
;                     if (ap) *(u32x4*)(ap + (size_t)row * 1024 + c) = pack8(v);
;                 }
;                 s = xor16_32(s);
;                 if (fq == 0) ssq[(size_t)row * 16 + u.pn * 4 + wc] = s;
	v_pk_fma_f32 v[28:29], v[28:29], v[76:77], v[228:229]
	v_pk_fma_f32 v[30:31], v[30:31], v[78:79], v[230:231]
	global_store_dwordx4 v207, v[28:31], s[92:93]
	v_mul_f32_e32 v210, v29, v29
	v_fmac_f32_e32 v210, v28, v28
	v_fmac_f32_e32 v210, v30, v30
	v_fmac_f32_e32 v210, v31, v31
	v_pk_mul_f32 v[228:229], v[100:101], v[28:29]
	v_pk_mul_f32 v[230:231], v[102:103], v[30:31]
	v_pk_fma_f32 v[24:25], v[24:25], v[72:73], v[232:233]
	v_pk_fma_f32 v[26:27], v[26:27], v[74:75], v[234:235]
	global_store_dwordx4 v207, v[24:27], s[92:93] offset:16
	v_fmac_f32_e32 v210, v24, v24
	v_fmac_f32_e32 v210, v25, v25
	v_fmac_f32_e32 v210, v26, v26
	v_fmac_f32_e32 v210, v27, v27
	v_pk_mul_f32 v[232:233], v[98:99], v[24:25]
	v_pk_mul_f32 v[234:235], v[96:97], v[26:27]
	v_cvt_pk_bf16_f32 v228, v228, v229
	v_cvt_pk_bf16_f32 v229, v230, v231
	v_cvt_pk_bf16_f32 v230, v232, v233
	v_cvt_pk_bf16_f32 v231, v234, v235
	global_store_dwordx4 v208, v[228:231], s[64:65]
	v_pk_fma_f32 v[20:21], v[20:21], v[68:69], v[236:237]
	v_pk_fma_f32 v[22:23], v[22:23], v[70:71], v[238:239]
	global_store_dwordx4 v207, v[20:23], s[92:93] offset:512
	v_fmac_f32_e32 v210, v20, v20
	v_fmac_f32_e32 v210, v21, v21
	v_fmac_f32_e32 v210, v22, v22
	v_fmac_f32_e32 v210, v23, v23
	v_pk_mul_f32 v[236:237], v[86:87], v[20:21]
	v_pk_mul_f32 v[238:239], v[84:85], v[22:23]
	v_pk_fma_f32 v[16:17], v[16:17], v[64:65], v[240:241]
	v_pk_fma_f32 v[18:19], v[18:19], v[66:67], v[242:243]
	global_store_dwordx4 v207, v[16:19], s[92:93] offset:528
	v_fmac_f32_e32 v210, v16, v16
	v_fmac_f32_e32 v210, v17, v17
	v_fmac_f32_e32 v210, v18, v18
	v_fmac_f32_e32 v210, v19, v19
	v_pk_mul_f32 v[240:241], v[80:81], v[16:17]
	v_pk_mul_f32 v[242:243], v[82:83], v[18:19]
	v_cvt_pk_bf16_f32 v236, v236, v237
	v_cvt_pk_bf16_f32 v237, v238, v239
	v_cvt_pk_bf16_f32 v238, v240, v241
	v_cvt_pk_bf16_f32 v239, v242, v243
	global_store_dwordx4 v208, v[236:239], s[64:65] offset:256
	ds_bpermute_b32 v211, v203, v210
	v_add_u32_e32 v207, 0x10000, v207
	s_waitcnt lgkmcnt(0)
	v_add_f32_e32 v211, v210, v211
	ds_bpermute_b32 v212, v202, v211
	v_add_u32_e32 v208, 0x8000, v208
	s_waitcnt lgkmcnt(0)
	v_add_f32_e32 v211, v211, v212
	s_mov_b64 exec, 0xffff
	global_store_dword v209, v211, s[90:91]
	s_mov_b64 exec, -1
	v_add_u32_e32 v209, 0x400, v209
	s_waitcnt vmcnt(8)
	v_pk_fma_f32 v[12:13], v[12:13], v[76:77], v[244:245]
	v_pk_fma_f32 v[14:15], v[14:15], v[78:79], v[246:247]
	global_store_dwordx4 v207, v[12:15], s[92:93]
	v_mul_f32_e32 v210, v13, v13
	v_fmac_f32_e32 v210, v12, v12
	v_fmac_f32_e32 v210, v14, v14
	v_fmac_f32_e32 v210, v15, v15
	v_pk_mul_f32 v[244:245], v[100:101], v[12:13]
	v_pk_mul_f32 v[246:247], v[102:103], v[14:15]
	v_pk_fma_f32 v[8:9], v[8:9], v[72:73], v[248:249]
	v_pk_fma_f32 v[10:11], v[10:11], v[74:75], v[250:251]
	global_store_dwordx4 v207, v[8:11], s[92:93] offset:16
	v_fmac_f32_e32 v210, v8, v8
	v_fmac_f32_e32 v210, v9, v9
	v_fmac_f32_e32 v210, v10, v10
	v_fmac_f32_e32 v210, v11, v11
	v_pk_mul_f32 v[248:249], v[98:99], v[8:9]
	v_pk_mul_f32 v[250:251], v[96:97], v[10:11]
	v_cvt_pk_bf16_f32 v244, v244, v245
	v_cvt_pk_bf16_f32 v245, v246, v247
	v_cvt_pk_bf16_f32 v246, v248, v249
	v_cvt_pk_bf16_f32 v247, v250, v251
	global_store_dwordx4 v208, v[244:247], s[64:65]
	v_pk_fma_f32 v[4:5], v[4:5], v[68:69], v[216:217]
	v_pk_fma_f32 v[6:7], v[6:7], v[70:71], v[218:219]
	global_store_dwordx4 v207, v[4:7], s[92:93] offset:512
	v_fmac_f32_e32 v210, v4, v4
	v_fmac_f32_e32 v210, v5, v5
	v_fmac_f32_e32 v210, v6, v6
	v_fmac_f32_e32 v210, v7, v7
	v_pk_mul_f32 v[216:217], v[86:87], v[4:5]
	v_pk_mul_f32 v[218:219], v[84:85], v[6:7]
	v_pk_fma_f32 v[0:1], v[0:1], v[64:65], v[220:221]
	v_pk_fma_f32 v[2:3], v[2:3], v[66:67], v[222:223]
	global_store_dwordx4 v207, v[0:3], s[92:93] offset:528
	v_fmac_f32_e32 v210, v0, v0
	v_fmac_f32_e32 v210, v1, v1
	v_fmac_f32_e32 v210, v2, v2
	v_fmac_f32_e32 v210, v3, v3
	v_pk_mul_f32 v[220:221], v[80:81], v[0:1]
	v_pk_mul_f32 v[222:223], v[82:83], v[2:3]
	v_cvt_pk_bf16_f32 v216, v216, v217
	v_cvt_pk_bf16_f32 v217, v218, v219
	v_cvt_pk_bf16_f32 v218, v220, v221
	v_cvt_pk_bf16_f32 v219, v222, v223
	global_store_dwordx4 v208, v[216:219], s[64:65] offset:256
	ds_bpermute_b32 v211, v203, v210
	s_waitcnt lgkmcnt(0)
	v_add_f32_e32 v211, v210, v211
	ds_bpermute_b32 v212, v202, v211
	s_waitcnt lgkmcnt(0)
	v_add_f32_e32 v211, v211, v212
	s_mov_b64 exec, 0xffff
	global_store_dword v209, v211, s[90:91]
	s_mov_b64 exec, -1
	s_andn2_b64 vcc, exec, s[0:1]
	s_mov_b64 s[0:1], -1
	s_cbranch_vccnz .LBB0_1083
	s_andn2_b64 vcc, exec, s[4:5]
	s_cbranch_vccnz .LBB0_1082
	s_barrier
	s_branch .LBB0_1082

;     DI void operator()(AccRef acc, const Unit& u, int wr, int wc, int fr, int fq) const {
;     ...
;         for (int ai = 0; ai < 2; ++ai) {
;             const int rb = u.pm * 256 + ai * 128 + wr * 64 + fr;
;             int mb, pos0, kv0; row_info(rb, mb, pos0, kv0);
;             f32x4 gt[2][2], gs[2][2];
; #pragma unroll
;             for (int bj = 0; bj < 2; ++bj)
; #pragma unroll
;                 for (int n = 0; n < 2; ++n) {
;                     const int c = u.pn * 256 + bj * 128 + cl + 4 * n;
;                     gt[bj][n] = *(const f32x4*)(gate + (size_t)mb * 6144 + c);
;                     if (ap) { const f32x4 g = *(const f32x4*)(gn + c), s = *(const f32x4*)(scn + (size_t)mb * 6144 + c); gs[bj][n] = g * (s + 1.f); }
;                 }
; #pragma unroll
;             for (int m = 0; m < 4; ++m) {
;                 const int row = rb + 16 * m;
;                 const float* xi = row < MP ? xin_p + (size_t)row * 1024 : xin_s + (size_t)(row - MP) * 1024;
;                 float s = 0.f;
; #pragma unroll
;                 for (int bj = 0; bj < 2; ++bj) {
;                     const int c = u.pn * 256 + bj * 128 + cl;
;                     float v[8];
; #pragma unroll
;                     for (int n = 0; n < 2; ++n) {
;                         const f32x4 x = *(const f32x4*)(xi + c + 4 * n);
;                         const f32x4 y = x + gt[bj][n] * acc[ai][bj][m][n];
;                         *(f32x4*)(xout + (size_t)row * 1024 + c + 4 * n) = y;
.LBB0_1303:
	v_readlane_b32 s1, v253, 32
	v_mbcnt_lo_u32_b32 v100, -1, 0
	v_mbcnt_hi_u32_b32 v100, -1, v100
	s_mov_b32 s1, s28
	v_and_b32_e32 v202, 15, v100
	v_bfe_u32 v204, v100, 4, 2
	s_mov_b32 s12, s34
	s_lshl_b32 s16, s16, 8
	s_lshl_b32 s1, s1, 6
	s_add_i32 s1, s1, s16
	v_add_u32_e32 v192, s1, v202
	s_lshl_b32 s13, s12, 5
	s_lshl_b32 s1, s0, 8
	v_add_u32_e32 v224, 0xffffc000, v192
	s_add_i32 s13, s13, s1
	v_lshrrev_b32_e32 v101, 6, v224
	v_lshl_add_u32 v188, v204, 3, s13
	v_ashrrev_i32_e32 v100, 11, v192
	v_add_u32_e32 v101, 8, v101
	v_cmp_gt_i32_e32 vcc, s94, v192
	v_mov_b64_e32 v[102:103], s[56:57]
	v_ashrrev_i32_e32 v189, 31, v188
	v_cndmask_b32_e32 v104, v101, v100, vcc
	v_mov_b64_e32 v[100:101], s[6:7]
	v_mad_i64_i32 v[100:101], s[16:17], v104, s75, v[100:101]
	v_mad_i64_i32 v[102:103], s[16:17], v104, s75, v[102:103]
	v_lshlrev_b64 v[190:191], 2, v[188:189]
	v_lshl_add_u64 v[104:105], v[100:101], 0, v[190:191]
	v_lshl_add_u64 v[194:195], s[72:73], 0, v[190:191]
	v_lshl_add_u64 v[168:169], v[102:103], 0, v[190:191]
	global_load_dwordx4 v[108:111], v[104:105], off offset:16
	global_load_dwordx4 v[116:119], v[104:105], off
	global_load_dwordx4 v[148:151], v[194:195], off offset:16
	global_load_dwordx4 v[164:167], v[194:195], off
	global_load_dwordx4 v[160:163], v[168:169], off offset:16
	global_load_dwordx4 v[172:175], v[168:169], off
	global_load_dwordx4 v[100:103], v[104:105], off offset:528
	s_nop 0
	global_load_dwordx4 v[104:107], v[104:105], off offset:512
	s_nop 0
	global_load_dwordx4 v[144:147], v[194:195], off offset:528
	global_load_dwordx4 v[156:159], v[194:195], off offset:512
	global_load_dwordx4 v[152:155], v[168:169], off offset:528
	s_nop 0
	global_load_dwordx4 v[168:171], v[168:169], off offset:512
	s_movk_i32 s1, 0x3fff
	v_cmp_lt_i32_e32 vcc, s1, v192
	s_and_saveexec_b64 s[16:17], vcc
	s_xor_b64 s[16:17], exec, s[16:17]
	v_lshlrev_b64 v[196:197], 12, v[224:225]
	v_mov_b32_e32 v193, v225
	v_lshl_add_u64 v[198:199], s[20:21], 0, v[196:197]
	v_lshlrev_b64 v[196:197], 12, v[192:193]
	s_andn2_saveexec_b64 s[16:17], s[16:17]
	v_ashrrev_i32_e32 v193, 31, v192
	v_lshlrev_b64 v[196:197], 12, v[192:193]
	v_lshl_add_u64 v[198:199], s[42:43], 0, v[196:197]
	s_or_b64 exec, exec, s[16:17]
	s_sub_u32 s82, s20, 0x4000000
	s_subb_u32 s83, s21, 0
	s_cmp_ge_u32 s16, 0x4000
	s_cselect_b32 s82, s82, s42
	s_cselect_b32 s83, s83, s43
	v_lshl_add_u32 v206, v192, 12, v190
	v_lshlrev_b32_e32 v213, 11, v192
	v_lshlrev_b32_e32 v209, 6, v192
	v_mov_b32_e32 v207, v206
	v_lshl_add_u32 v208, v188, 1, v213
	global_load_dwordx4 v[232:235], v206, s[82:83] offset:16
	global_load_dwordx4 v[240:243], v206, s[82:83] offset:528
	global_load_dwordx4 v[228:231], v206, s[82:83]
	global_load_dwordx4 v[236:239], v206, s[82:83] offset:512
	v_add_u32_e32 v206, 0x10000, v206
	global_load_dwordx4 v[248:251], v206, s[82:83] offset:16
	global_load_dwordx4 v[220:223], v206, s[82:83] offset:528
	global_load_dwordx4 v[244:247], v206, s[82:83]
	global_load_dwordx4 v[216:219], v206, s[82:83] offset:512
	v_add_u32_e32 v206, 0x10000, v206
	s_waitcnt vmcnt(8)
	v_pk_add_f32 v[172:173], v[172:173], 1.0 op_sel_hi:[1,0]
	v_pk_add_f32 v[154:155], v[154:155], 1.0 op_sel_hi:[1,0]
	v_pk_mul_f32 v[164:165], v[164:165], v[172:173]
	v_pk_add_f32 v[172:173], v[160:161], 1.0 op_sel_hi:[1,0]
	v_pk_add_f32 v[160:161], v[162:163], 1.0 op_sel_hi:[1,0]
	v_pk_mul_f32 v[162:163], v[148:149], v[172:173]
	v_pk_mul_f32 v[160:161], v[150:151], v[160:161]
	v_pk_add_f32 v[148:149], v[170:171], 1.0 op_sel_hi:[1,0]
	v_pk_add_f32 v[150:151], v[168:169], 1.0 op_sel_hi:[1,0]
	v_pk_mul_f32 v[146:147], v[146:147], v[154:155]
	v_lshl_add_u64 v[154:155], v[198:199], 0, v[190:191]
	v_pk_mul_f32 v[148:149], v[158:159], v[148:149]
	v_pk_mul_f32 v[150:151], v[156:157], v[150:151]
	v_pk_add_f32 v[174:175], v[174:175], 1.0 op_sel_hi:[1,0]
	v_pk_add_f32 v[152:153], v[152:153], 1.0 op_sel_hi:[1,0]
	v_pk_mul_f32 v[166:167], v[166:167], v[174:175]
	v_pk_mul_f32 v[144:145], v[144:145], v[152:153]
	v_lshlrev_b64 v[152:153], 11, v[192:193]
	v_lshl_add_u64 v[152:153], s[58:59], 0, v[152:153]
	v_lshlrev_b32_e32 v202, 2, v202
	v_lshl_add_u32 v202, v204, 6, v202
	v_xor_b32_e32 v203, 64, v202
	s_lshl_b32 s0, s0, 2
	v_xor_b32_e32 v202, 0x80, v202
	s_ashr_i32 s1, s0, 31
	s_ashr_i32 s13, s12, 31
	s_lshl_b64 s[0:1], s[0:1], 2
	s_add_u32 s16, s37, s0
	s_addc_u32 s17, s38, s1
	s_lshl_b64 s[0:1], s[12:13], 2
	s_add_u32 s90, s16, s0
	v_cmp_eq_u32_e32 vcc, 0, v204
	s_addc_u32 s91, s17, s1
	s_waitcnt vmcnt(4)
; DI u32x4 pack8(const float* v) { u32x4 w; w.x = pk2(v[0], v[1]); w.y = pk2(v[2], v[3]); w.z = pk2(v[4], v[5]); w.w = pk2(v[6], v[7]); return w; }
; #define xor16_32(s) xor16_32_l((s), fr + 16 * fq)
;     DI void operator()(AccRef acc, const Unit& u, int wr, int wc, int fr, int fq) const {
;     ...
;             for (int m = 0; m < 4; ++m) {
;                 const int row = rb + 16 * m;
;                 const float* xi = row < MP ? xin_p + (size_t)row * 1024 : xin_s + (size_t)(row - MP) * 1024;
;                 float s = 0.f;
; #pragma unroll
;                 for (int bj = 0; bj < 2; ++bj) {
;                     const int c = u.pn * 256 + bj * 128 + cl;
;                     float v[8];
; #pragma unroll
;                     for (int n = 0; n < 2; ++n) {
;                         const f32x4 x = *(const f32x4*)(xi + c + 4 * n);
;                         const f32x4 y = x + gt[bj][n] * acc[ai][bj][m][n];
;                         *(f32x4*)(xout + (size_t)row * 1024 + c + 4 * n) = y;
; #pragma unroll
;                         for (int j = 0; j < 4; ++j) { s += y[j] * y[j]; v[4 * n + j] = ap ? y[j] * gs[bj][n][j] : 0.f; }
;                     }
;                     if (ap) *(u32x4*)(ap + (size_t)row * 1024 + c) = pack8(v);
;                 }
;                 s = xor16_32(s);
;                 if (fq == 0) ssq[(size_t)row * 16 + u.pn * 4 + wc] = s;
	v_pk_fma_f32 v[140:141], v[140:141], v[116:117], v[228:229]
	v_pk_fma_f32 v[142:143], v[142:143], v[118:119], v[230:231]
	global_store_dwordx4 v207, v[140:143], s[92:93]
	v_mul_f32_e32 v210, v141, v141
	v_fmac_f32_e32 v210, v140, v140
	v_fmac_f32_e32 v210, v142, v142
	v_fmac_f32_e32 v210, v143, v143
	v_pk_mul_f32 v[228:229], v[164:165], v[140:141]
	v_pk_mul_f32 v[230:231], v[166:167], v[142:143]
	v_pk_fma_f32 v[136:137], v[136:137], v[108:109], v[232:233]
	v_pk_fma_f32 v[138:139], v[138:139], v[110:111], v[234:235]
	global_store_dwordx4 v207, v[136:139], s[92:93] offset:16
	v_fmac_f32_e32 v210, v136, v136
	v_fmac_f32_e32 v210, v137, v137
	v_fmac_f32_e32 v210, v138, v138
	v_fmac_f32_e32 v210, v139, v139
	v_pk_mul_f32 v[232:233], v[162:163], v[136:137]
	v_pk_mul_f32 v[234:235], v[160:161], v[138:139]
	v_cvt_pk_bf16_f32 v228, v228, v229
	v_cvt_pk_bf16_f32 v229, v230, v231
	v_cvt_pk_bf16_f32 v230, v232, v233
	v_cvt_pk_bf16_f32 v231, v234, v235
	global_store_dwordx4 v208, v[228:231], s[58:59]
	v_pk_fma_f32 v[132:133], v[132:133], v[104:105], v[236:237]
	v_pk_fma_f32 v[134:135], v[134:135], v[106:107], v[238:239]
	global_store_dwordx4 v207, v[132:135], s[92:93] offset:512
	v_fmac_f32_e32 v210, v132, v132
	v_fmac_f32_e32 v210, v133, v133
	v_fmac_f32_e32 v210, v134, v134
	v_fmac_f32_e32 v210, v135, v135
	v_pk_mul_f32 v[236:237], v[150:151], v[132:133]
	v_pk_mul_f32 v[238:239], v[148:149], v[134:135]
	v_pk_fma_f32 v[128:129], v[128:129], v[100:101], v[240:241]
	v_pk_fma_f32 v[130:131], v[130:131], v[102:103], v[242:243]
	global_store_dwordx4 v207, v[128:131], s[92:93] offset:528
	v_fmac_f32_e32 v210, v128, v128
	v_fmac_f32_e32 v210, v129, v129
	v_fmac_f32_e32 v210, v130, v130
	v_fmac_f32_e32 v210, v131, v131
	v_pk_mul_f32 v[240:241], v[144:145], v[128:129]
	v_pk_mul_f32 v[242:243], v[146:147], v[130:131]
	v_cvt_pk_bf16_f32 v236, v236, v237
	v_cvt_pk_bf16_f32 v237, v238, v239
	v_cvt_pk_bf16_f32 v238, v240, v241
	v_cvt_pk_bf16_f32 v239, v242, v243
	global_store_dwordx4 v208, v[236:239], s[58:59] offset:256
	ds_bpermute_b32 v211, v203, v210
	v_add_u32_e32 v207, 0x10000, v207
	global_load_dwordx4 v[232:235], v206, s[82:83] offset:16
	global_load_dwordx4 v[240:243], v206, s[82:83] offset:528
	global_load_dwordx4 v[228:231], v206, s[82:83]
	global_load_dwordx4 v[236:239], v206, s[82:83] offset:512
	s_waitcnt lgkmcnt(0)
	v_add_f32_e32 v211, v210, v211
	ds_bpermute_b32 v212, v202, v211
	v_add_u32_e32 v208, 0x8000, v208
	s_waitcnt lgkmcnt(0)
	v_add_f32_e32 v211, v211, v212
	s_mov_b64 exec, 0xffff
	global_store_dword v209, v211, s[90:91]
	s_mov_b64 exec, -1
	v_add_u32_e32 v209, 0x400, v209
	s_waitcnt vmcnt(11)
	v_pk_fma_f32 v[124:125], v[124:125], v[116:117], v[244:245]
	v_pk_fma_f32 v[126:127], v[126:127], v[118:119], v[246:247]
	global_store_dwordx4 v207, v[124:127], s[92:93]
	v_mul_f32_e32 v210, v125, v125
	v_fmac_f32_e32 v210, v124, v124
	v_fmac_f32_e32 v210, v126, v126
	v_fmac_f32_e32 v210, v127, v127
	v_pk_mul_f32 v[244:245], v[164:165], v[124:125]
	v_pk_mul_f32 v[246:247], v[166:167], v[126:127]
	v_pk_fma_f32 v[120:121], v[120:121], v[108:109], v[248:249]
	v_pk_fma_f32 v[122:123], v[122:123], v[110:111], v[250:251]
	global_store_dwordx4 v207, v[120:123], s[92:93] offset:16
	v_fmac_f32_e32 v210, v120, v120
	v_fmac_f32_e32 v210, v121, v121
	v_fmac_f32_e32 v210, v122, v122
	v_fmac_f32_e32 v210, v123, v123
	v_pk_mul_f32 v[248:249], v[162:163], v[120:121]
	v_pk_mul_f32 v[250:251], v[160:161], v[122:123]
	v_cvt_pk_bf16_f32 v244, v244, v245
	v_cvt_pk_bf16_f32 v245, v246, v247
	v_cvt_pk_bf16_f32 v246, v248, v249
	v_cvt_pk_bf16_f32 v247, v250, v251
	global_store_dwordx4 v208, v[244:247], s[58:59]
	v_pk_fma_f32 v[112:113], v[112:113], v[104:105], v[216:217]
	v_pk_fma_f32 v[114:115], v[114:115], v[106:107], v[218:219]
	global_store_dwordx4 v207, v[112:115], s[92:93] offset:512
	v_fmac_f32_e32 v210, v112, v112
	v_fmac_f32_e32 v210, v113, v113
	v_fmac_f32_e32 v210, v114, v114
	v_fmac_f32_e32 v210, v115, v115
	v_pk_mul_f32 v[216:217], v[150:151], v[112:113]
	v_pk_mul_f32 v[218:219], v[148:149], v[114:115]
	v_pk_fma_f32 v[96:97], v[96:97], v[100:101], v[220:221]
	v_pk_fma_f32 v[98:99], v[98:99], v[102:103], v[222:223]
	global_store_dwordx4 v207, v[96:99], s[92:93] offset:528
	v_fmac_f32_e32 v210, v96, v96
	v_fmac_f32_e32 v210, v97, v97
	v_fmac_f32_e32 v210, v98, v98
	v_fmac_f32_e32 v210, v99, v99
	v_pk_mul_f32 v[220:221], v[144:145], v[96:97]
	v_pk_mul_f32 v[222:223], v[146:147], v[98:99]
	v_cvt_pk_bf16_f32 v216, v216, v217
	v_cvt_pk_bf16_f32 v217, v218, v219
	v_cvt_pk_bf16_f32 v218, v220, v221
	v_cvt_pk_bf16_f32 v219, v222, v223
	global_store_dwordx4 v208, v[216:219], s[58:59] offset:256
	ds_bpermute_b32 v211, v203, v210
	v_add_u32_e32 v207, 0x10000, v207
	v_add_u32_e32 v206, 0x10000, v206
	global_load_dwordx4 v[248:251], v206, s[82:83] offset:16
	global_load_dwordx4 v[220:223], v206, s[82:83] offset:528
	global_load_dwordx4 v[244:247], v206, s[82:83]
	global_load_dwordx4 v[216:219], v206, s[82:83] offset:512
	s_waitcnt lgkmcnt(0)
	v_add_f32_e32 v211, v210, v211
	ds_bpermute_b32 v212, v202, v211
	v_add_u32_e32 v208, 0x8000, v208
	s_waitcnt lgkmcnt(0)
	v_add_f32_e32 v211, v211, v212
	s_mov_b64 exec, 0xffff
	global_store_dword v209, v211, s[90:91]
	s_mov_b64 exec, -1
	v_add_u32_e32 v209, 0x400, v209
	s_waitcnt vmcnt(12)
; DI u32x4 pack8(const float* v) { u32x4 w; w.x = pk2(v[0], v[1]); w.y = pk2(v[2], v[3]); w.z = pk2(v[4], v[5]); w.w = pk2(v[6], v[7]); return w; }
; #define xor16_32(s) xor16_32_l((s), fr + 16 * fq)
;     DI void operator()(AccRef acc, const Unit& u, int wr, int wc, int fr, int fq) const {
;     ...
;             for (int m = 0; m < 4; ++m) {
;                 const int row = rb + 16 * m;
;                 const float* xi = row < MP ? xin_p + (size_t)row * 1024 : xin_s + (size_t)(row - MP) * 1024;
;                 float s = 0.f;
; #pragma unroll
;                 for (int bj = 0; bj < 2; ++bj) {
;                     const int c = u.pn * 256 + bj * 128 + cl;
;                     float v[8];
; #pragma unroll
;                     for (int n = 0; n < 2; ++n) {
;                         const f32x4 x = *(const f32x4*)(xi + c + 4 * n);
;                         const f32x4 y = x + gt[bj][n] * acc[ai][bj][m][n];
;                         *(f32x4*)(xout + (size_t)row * 1024 + c + 4 * n) = y;
; #pragma unroll
;                         for (int j = 0; j < 4; ++j) { s += y[j] * y[j]; v[4 * n + j] = ap ? y[j] * gs[bj][n][j] : 0.f; }
;                     }
;                     if (ap) *(u32x4*)(ap + (size_t)row * 1024 + c) = pack8(v);
;                 }
;                 s = xor16_32(s);
;                 if (fq == 0) ssq[(size_t)row * 16 + u.pn * 4 + wc] = s;
	v_pk_fma_f32 v[92:93], v[92:93], v[116:117], v[228:229]
	v_pk_fma_f32 v[94:95], v[94:95], v[118:119], v[230:231]
	global_store_dwordx4 v207, v[92:95], s[92:93]
	v_mul_f32_e32 v210, v93, v93
	v_fmac_f32_e32 v210, v92, v92
	v_fmac_f32_e32 v210, v94, v94
	v_fmac_f32_e32 v210, v95, v95
	v_pk_mul_f32 v[228:229], v[164:165], v[92:93]
	v_pk_mul_f32 v[230:231], v[166:167], v[94:95]
	v_pk_fma_f32 v[88:89], v[88:89], v[108:109], v[232:233]
	v_pk_fma_f32 v[90:91], v[90:91], v[110:111], v[234:235]
	global_store_dwordx4 v207, v[88:91], s[92:93] offset:16
	v_fmac_f32_e32 v210, v88, v88
	v_fmac_f32_e32 v210, v89, v89
	v_fmac_f32_e32 v210, v90, v90
	v_fmac_f32_e32 v210, v91, v91
	v_pk_mul_f32 v[232:233], v[162:163], v[88:89]
	v_pk_mul_f32 v[234:235], v[160:161], v[90:91]
	v_cvt_pk_bf16_f32 v228, v228, v229
	v_cvt_pk_bf16_f32 v229, v230, v231
	v_cvt_pk_bf16_f32 v230, v232, v233
	v_cvt_pk_bf16_f32 v231, v234, v235
	global_store_dwordx4 v208, v[228:231], s[58:59]
	v_pk_fma_f32 v[84:85], v[84:85], v[104:105], v[236:237]
	v_pk_fma_f32 v[86:87], v[86:87], v[106:107], v[238:239]
	global_store_dwordx4 v207, v[84:87], s[92:93] offset:512
	v_fmac_f32_e32 v210, v84, v84
	v_fmac_f32_e32 v210, v85, v85
	v_fmac_f32_e32 v210, v86, v86
	v_fmac_f32_e32 v210, v87, v87
	v_pk_mul_f32 v[236:237], v[150:151], v[84:85]
	v_pk_mul_f32 v[238:239], v[148:149], v[86:87]
	v_pk_fma_f32 v[80:81], v[80:81], v[100:101], v[240:241]
	v_pk_fma_f32 v[82:83], v[82:83], v[102:103], v[242:243]
	global_store_dwordx4 v207, v[80:83], s[92:93] offset:528
	v_fmac_f32_e32 v210, v80, v80
	v_fmac_f32_e32 v210, v81, v81
	v_fmac_f32_e32 v210, v82, v82
	v_fmac_f32_e32 v210, v83, v83
	v_pk_mul_f32 v[240:241], v[144:145], v[80:81]
	v_pk_mul_f32 v[242:243], v[146:147], v[82:83]
	v_cvt_pk_bf16_f32 v236, v236, v237
	v_cvt_pk_bf16_f32 v237, v238, v239
	v_cvt_pk_bf16_f32 v238, v240, v241
	v_cvt_pk_bf16_f32 v239, v242, v243
	global_store_dwordx4 v208, v[236:239], s[58:59] offset:256
	ds_bpermute_b32 v211, v203, v210
	v_add_u32_e32 v207, 0x10000, v207
	v_add_u32_e32 v206, 0x50000, v206
	global_load_dwordx4 v[232:235], v206, s[82:83] offset:16
	global_load_dwordx4 v[240:243], v206, s[82:83] offset:528
	global_load_dwordx4 v[228:231], v206, s[82:83]
	global_load_dwordx4 v[236:239], v206, s[82:83] offset:512
	s_waitcnt lgkmcnt(0)
	v_add_f32_e32 v211, v210, v211
	ds_bpermute_b32 v212, v202, v211
	v_add_u32_e32 v208, 0x8000, v208
	s_waitcnt lgkmcnt(0)
	v_add_f32_e32 v211, v211, v212
	s_mov_b64 exec, 0xffff
	global_store_dword v209, v211, s[90:91]
	s_mov_b64 exec, -1
	v_add_u32_e32 v209, 0x400, v209
	s_waitcnt vmcnt(12)
	v_pk_fma_f32 v[76:77], v[76:77], v[116:117], v[244:245]
	v_pk_fma_f32 v[78:79], v[78:79], v[118:119], v[246:247]
	global_store_dwordx4 v207, v[76:79], s[92:93]
	v_mul_f32_e32 v210, v77, v77
	v_fmac_f32_e32 v210, v76, v76
	v_fmac_f32_e32 v210, v78, v78
	v_fmac_f32_e32 v210, v79, v79
	v_pk_mul_f32 v[244:245], v[164:165], v[76:77]
	v_pk_mul_f32 v[246:247], v[166:167], v[78:79]
	v_pk_fma_f32 v[72:73], v[72:73], v[108:109], v[248:249]
	v_pk_fma_f32 v[74:75], v[74:75], v[110:111], v[250:251]
	global_store_dwordx4 v207, v[72:75], s[92:93] offset:16
	v_fmac_f32_e32 v210, v72, v72
	v_fmac_f32_e32 v210, v73, v73
	v_fmac_f32_e32 v210, v74, v74
	v_fmac_f32_e32 v210, v75, v75
	v_pk_mul_f32 v[248:249], v[162:163], v[72:73]
	v_pk_mul_f32 v[250:251], v[160:161], v[74:75]
	v_cvt_pk_bf16_f32 v244, v244, v245
	v_cvt_pk_bf16_f32 v245, v246, v247
	v_cvt_pk_bf16_f32 v246, v248, v249
	v_cvt_pk_bf16_f32 v247, v250, v251
	global_store_dwordx4 v208, v[244:247], s[58:59]
	v_pk_fma_f32 v[68:69], v[68:69], v[104:105], v[216:217]
	v_pk_fma_f32 v[70:71], v[70:71], v[106:107], v[218:219]
	global_store_dwordx4 v207, v[68:71], s[92:93] offset:512
	v_fmac_f32_e32 v210, v68, v68
	v_fmac_f32_e32 v210, v69, v69
	v_fmac_f32_e32 v210, v70, v70
	v_fmac_f32_e32 v210, v71, v71
	v_pk_mul_f32 v[216:217], v[150:151], v[68:69]
	v_pk_mul_f32 v[218:219], v[148:149], v[70:71]
	v_pk_fma_f32 v[64:65], v[64:65], v[100:101], v[220:221]
	v_pk_fma_f32 v[66:67], v[66:67], v[102:103], v[222:223]
	global_store_dwordx4 v207, v[64:67], s[92:93] offset:528
	v_fmac_f32_e32 v210, v64, v64
	v_fmac_f32_e32 v210, v65, v65
	v_fmac_f32_e32 v210, v66, v66
	v_fmac_f32_e32 v210, v67, v67
	v_pk_mul_f32 v[220:221], v[144:145], v[64:65]
	v_pk_mul_f32 v[222:223], v[146:147], v[66:67]
	v_cvt_pk_bf16_f32 v216, v216, v217
	v_cvt_pk_bf16_f32 v217, v218, v219
	v_cvt_pk_bf16_f32 v218, v220, v221
	v_cvt_pk_bf16_f32 v219, v222, v223
	global_store_dwordx4 v208, v[216:219], s[58:59] offset:256
	ds_bpermute_b32 v211, v203, v210
	v_add_u32_e32 v207, 0x50000, v207
	v_add_u32_e32 v206, 0x10000, v206
	global_load_dwordx4 v[248:251], v206, s[82:83] offset:16
	global_load_dwordx4 v[220:223], v206, s[82:83] offset:528
	global_load_dwordx4 v[244:247], v206, s[82:83]
	global_load_dwordx4 v[216:219], v206, s[82:83] offset:512
	s_waitcnt lgkmcnt(0)
	v_add_f32_e32 v211, v210, v211
	ds_bpermute_b32 v212, v202, v211
	v_add_u32_e32 v208, 0x28000, v208
	s_waitcnt lgkmcnt(0)
	v_add_f32_e32 v211, v211, v212
	s_mov_b64 exec, 0xffff
	global_store_dword v209, v211, s[90:91]
	s_mov_b64 exec, -1
	v_add_u32_e32 v209, 0x1400, v209
	v_add_u32_e32 v224, 0xffffc080, v192
	v_add_u32_e32 v112, 0x80, v192
	s_waitcnt lgkmcnt(0)
; DI u32x4 pack8(const float* v) { u32x4 w; w.x = pk2(v[0], v[1]); w.y = pk2(v[2], v[3]); w.z = pk2(v[4], v[5]); w.w = pk2(v[6], v[7]); return w; }
; #define xor16_32(s) xor16_32_l((s), fr + 16 * fq)
;     DI void operator()(AccRef acc, const Unit& u, int wr, int wc, int fr, int fq) const {
;     ...
;         for (int ai = 0; ai < 2; ++ai) {
;             const int rb = u.pm * 256 + ai * 128 + wr * 64 + fr;
;             int mb, pos0, kv0; row_info(rb, mb, pos0, kv0);
;             f32x4 gt[2][2], gs[2][2];
; #pragma unroll
;             for (int bj = 0; bj < 2; ++bj)
; #pragma unroll
;                 for (int n = 0; n < 2; ++n) {
;                     const int c = u.pn * 256 + bj * 128 + cl + 4 * n;
;                     gt[bj][n] = *(const f32x4*)(gate + (size_t)mb * 6144 + c);
;                     if (ap) { const f32x4 g = *(const f32x4*)(gn + c), s = *(const f32x4*)(scn + (size_t)mb * 6144 + c); gs[bj][n] = g * (s + 1.f); }
;                 }
; #pragma unroll
;             for (int m = 0; m < 4; ++m) {
;                 const int row = rb + 16 * m;
;                 const float* xi = row < MP ? xin_p + (size_t)row * 1024 : xin_s + (size_t)(row - MP) * 1024;
;                 float s = 0.f;
; #pragma unroll
;                 for (int bj = 0; bj < 2; ++bj) {
;                     const int c = u.pn * 256 + bj * 128 + cl;
;                     float v[8];
; #pragma unroll
;                     for (int n = 0; n < 2; ++n) {
;                         const f32x4 x = *(const f32x4*)(xi + c + 4 * n);
;                         const f32x4 y = x + gt[bj][n] * acc[ai][bj][m][n];
;                         *(f32x4*)(xout + (size_t)row * 1024 + c + 4 * n) = y;
; #pragma unroll
;                         for (int j = 0; j < 4; ++j) { s += y[j] * y[j]; v[4 * n + j] = ap ? y[j] * gs[bj][n][j] : 0.f; }
;                     }
;                     if (ap) *(u32x4*)(ap + (size_t)row * 1024 + c) = pack8(v);
;                 }
;                 s = xor16_32(s);
;                 if (fq == 0) ssq[(size_t)row * 16 + u.pn * 4 + wc] = s;
	v_lshrrev_b32_e32 v65, 6, v224
	v_ashrrev_i32_e32 v64, 11, v112
	v_add_u32_e32 v65, 8, v65
	v_cmp_gt_i32_e64 s[0:1], s94, v112
	v_mov_b64_e32 v[66:67], s[56:57]
	s_nop 0
	v_cndmask_b32_e64 v68, v65, v64, s[0:1]
	v_mov_b64_e32 v[64:65], s[6:7]
	v_mad_i64_i32 v[64:65], s[0:1], v68, s75, v[64:65]
	v_mad_i64_i32 v[66:67], s[0:1], v68, s75, v[66:67]
	v_lshl_add_u64 v[68:69], v[64:65], 0, v[190:191]
	v_lshl_add_u64 v[104:105], v[66:67], 0, v[190:191]
	global_load_dwordx4 v[72:75], v[68:69], off offset:16
	global_load_dwordx4 v[76:79], v[68:69], off
	global_load_dwordx4 v[84:87], v[194:195], off offset:16
	global_load_dwordx4 v[100:103], v[194:195], off
	global_load_dwordx4 v[96:99], v[104:105], off offset:16
	global_load_dwordx4 v[108:111], v[104:105], off
	global_load_dwordx4 v[64:67], v[68:69], off offset:528
	s_nop 0
	global_load_dwordx4 v[68:71], v[68:69], off offset:512
	s_nop 0
	global_load_dwordx4 v[80:83], v[194:195], off offset:528
	global_load_dwordx4 v[92:95], v[194:195], off offset:512
	global_load_dwordx4 v[88:91], v[104:105], off offset:528
	s_nop 0
	global_load_dwordx4 v[104:107], v[104:105], off offset:512
	s_movk_i32 s0, 0x3fff
	v_cmp_lt_i32_e64 s[0:1], s0, v112
	s_and_saveexec_b64 s[12:13], s[0:1]
	s_xor_b64 s[0:1], exec, s[12:13]
	v_lshlrev_b64 v[114:115], 12, v[224:225]
	v_mov_b32_e32 v113, v225
	v_lshl_add_u64 v[116:117], s[20:21], 0, v[114:115]
	v_lshlrev_b64 v[114:115], 12, v[112:113]
	s_andn2_saveexec_b64 s[0:1], s[0:1]
	v_ashrrev_i32_e32 v113, 31, v112
	v_lshlrev_b64 v[114:115], 12, v[112:113]
	v_lshl_add_u64 v[116:117], s[42:43], 0, v[114:115]
	s_or_b64 exec, exec, s[0:1]
	s_waitcnt vmcnt(6)
	v_pk_add_f32 v[108:109], v[108:109], 1.0 op_sel_hi:[1,0]
	s_waitcnt vmcnt(1)
	v_pk_add_f32 v[90:91], v[90:91], 1.0 op_sel_hi:[1,0]
	v_pk_mul_f32 v[100:101], v[100:101], v[108:109]
	v_pk_add_f32 v[108:109], v[96:97], 1.0 op_sel_hi:[1,0]
	v_pk_add_f32 v[96:97], v[98:99], 1.0 op_sel_hi:[1,0]
	v_pk_mul_f32 v[98:99], v[84:85], v[108:109]
	v_pk_mul_f32 v[96:97], v[86:87], v[96:97]
	s_waitcnt vmcnt(0)
	v_pk_add_f32 v[84:85], v[106:107], 1.0 op_sel_hi:[1,0]
	v_pk_add_f32 v[86:87], v[104:105], 1.0 op_sel_hi:[1,0]
	v_pk_mul_f32 v[82:83], v[82:83], v[90:91]
	v_lshl_add_u64 v[90:91], v[116:117], 0, v[190:191]
	v_pk_mul_f32 v[84:85], v[94:95], v[84:85]
	v_pk_mul_f32 v[86:87], v[92:93], v[86:87]
	v_pk_add_f32 v[110:111], v[110:111], 1.0 op_sel_hi:[1,0]
	v_pk_add_f32 v[88:89], v[88:89], 1.0 op_sel_hi:[1,0]
	v_pk_mul_f32 v[102:103], v[102:103], v[110:111]
	v_pk_mul_f32 v[80:81], v[80:81], v[88:89]
	v_lshlrev_b64 v[88:89], 11, v[112:113]
	v_lshl_add_u64 v[88:89], s[58:59], 0, v[88:89]
	v_pk_fma_f32 v[60:61], v[60:61], v[76:77], v[228:229]
	v_pk_fma_f32 v[62:63], v[62:63], v[78:79], v[230:231]
	global_store_dwordx4 v207, v[60:63], s[92:93]
	v_mul_f32_e32 v210, v61, v61
	v_fmac_f32_e32 v210, v60, v60
	v_fmac_f32_e32 v210, v62, v62
	v_fmac_f32_e32 v210, v63, v63
	v_pk_mul_f32 v[228:229], v[100:101], v[60:61]
	v_pk_mul_f32 v[230:231], v[102:103], v[62:63]
	v_pk_fma_f32 v[56:57], v[56:57], v[72:73], v[232:233]
	v_pk_fma_f32 v[58:59], v[58:59], v[74:75], v[234:235]
	global_store_dwordx4 v207, v[56:59], s[92:93] offset:16
	v_fmac_f32_e32 v210, v56, v56
	v_fmac_f32_e32 v210, v57, v57
	v_fmac_f32_e32 v210, v58, v58
	v_fmac_f32_e32 v210, v59, v59
	v_pk_mul_f32 v[232:233], v[98:99], v[56:57]
	v_pk_mul_f32 v[234:235], v[96:97], v[58:59]
	v_cvt_pk_bf16_f32 v228, v228, v229
	v_cvt_pk_bf16_f32 v229, v230, v231
	v_cvt_pk_bf16_f32 v230, v232, v233
	v_cvt_pk_bf16_f32 v231, v234, v235
	global_store_dwordx4 v208, v[228:231], s[58:59]
	v_pk_fma_f32 v[52:53], v[52:53], v[68:69], v[236:237]
	v_pk_fma_f32 v[54:55], v[54:55], v[70:71], v[238:239]
	global_store_dwordx4 v207, v[52:55], s[92:93] offset:512
	v_fmac_f32_e32 v210, v52, v52
	v_fmac_f32_e32 v210, v53, v53
	v_fmac_f32_e32 v210, v54, v54
	v_fmac_f32_e32 v210, v55, v55
	v_pk_mul_f32 v[236:237], v[86:87], v[52:53]
	v_pk_mul_f32 v[238:239], v[84:85], v[54:55]
	v_pk_fma_f32 v[48:49], v[48:49], v[64:65], v[240:241]
	v_pk_fma_f32 v[50:51], v[50:51], v[66:67], v[242:243]
	global_store_dwordx4 v207, v[48:51], s[92:93] offset:528
	v_fmac_f32_e32 v210, v48, v48
	v_fmac_f32_e32 v210, v49, v49
	v_fmac_f32_e32 v210, v50, v50
	v_fmac_f32_e32 v210, v51, v51
	v_pk_mul_f32 v[240:241], v[80:81], v[48:49]
	v_pk_mul_f32 v[242:243], v[82:83], v[50:51]
	v_cvt_pk_bf16_f32 v236, v236, v237
	v_cvt_pk_bf16_f32 v237, v238, v239
	v_cvt_pk_bf16_f32 v238, v240, v241
	v_cvt_pk_bf16_f32 v239, v242, v243
	global_store_dwordx4 v208, v[236:239], s[58:59] offset:256
	ds_bpermute_b32 v211, v203, v210
	v_add_u32_e32 v207, 0x10000, v207
	v_add_u32_e32 v206, 0x10000, v206
	global_load_dwordx4 v[232:235], v206, s[82:83] offset:16
	global_load_dwordx4 v[240:243], v206, s[82:83] offset:528
	global_load_dwordx4 v[228:231], v206, s[82:83]
	global_load_dwordx4 v[236:239], v206, s[82:83] offset:512
	s_waitcnt lgkmcnt(0)
	v_add_f32_e32 v211, v210, v211
	ds_bpermute_b32 v212, v202, v211
	v_add_u32_e32 v208, 0x8000, v208
	s_waitcnt lgkmcnt(0)
; DI u32x4 pack8(const float* v) { u32x4 w; w.x = pk2(v[0], v[1]); w.y = pk2(v[2], v[3]); w.z = pk2(v[4], v[5]); w.w = pk2(v[6], v[7]); return w; }
; #define xor16_32(s) xor16_32_l((s), fr + 16 * fq)
;     DI void operator()(AccRef acc, const Unit& u, int wr, int wc, int fr, int fq) const {
;     ...
;             for (int m = 0; m < 4; ++m) {
;                 const int row = rb + 16 * m;
;                 const float* xi = row < MP ? xin_p + (size_t)row * 1024 : xin_s + (size_t)(row - MP) * 1024;
;                 float s = 0.f;
; #pragma unroll
;                 for (int bj = 0; bj < 2; ++bj) {
;                     const int c = u.pn * 256 + bj * 128 + cl;
;                     float v[8];
; #pragma unroll
;                     for (int n = 0; n < 2; ++n) {
;                         const f32x4 x = *(const f32x4*)(xi + c + 4 * n);
;                         const f32x4 y = x + gt[bj][n] * acc[ai][bj][m][n];
;                         *(f32x4*)(xout + (size_t)row * 1024 + c + 4 * n) = y;
; #pragma unroll
;                         for (int j = 0; j < 4; ++j) { s += y[j] * y[j]; v[4 * n + j] = ap ? y[j] * gs[bj][n][j] : 0.f; }
;                     }
;                     if (ap) *(u32x4*)(ap + (size_t)row * 1024 + c) = pack8(v);
;                 }
;                 s = xor16_32(s);
;                 if (fq == 0) ssq[(size_t)row * 16 + u.pn * 4 + wc] = s;
	v_add_f32_e32 v211, v211, v212
	s_mov_b64 exec, 0xffff
	global_store_dword v209, v211, s[90:91]
	s_mov_b64 exec, -1
	v_add_u32_e32 v209, 0x400, v209
	v_pk_fma_f32 v[44:45], v[44:45], v[76:77], v[244:245]
	v_pk_fma_f32 v[46:47], v[46:47], v[78:79], v[246:247]
	global_store_dwordx4 v207, v[44:47], s[92:93]
	v_mul_f32_e32 v210, v45, v45
	v_fmac_f32_e32 v210, v44, v44
	v_fmac_f32_e32 v210, v46, v46
	v_fmac_f32_e32 v210, v47, v47
	v_pk_mul_f32 v[244:245], v[100:101], v[44:45]
	v_pk_mul_f32 v[246:247], v[102:103], v[46:47]
	v_pk_fma_f32 v[40:41], v[40:41], v[72:73], v[248:249]
	v_pk_fma_f32 v[42:43], v[42:43], v[74:75], v[250:251]
	global_store_dwordx4 v207, v[40:43], s[92:93] offset:16
	v_fmac_f32_e32 v210, v40, v40
	v_fmac_f32_e32 v210, v41, v41
	v_fmac_f32_e32 v210, v42, v42
	v_fmac_f32_e32 v210, v43, v43
	v_pk_mul_f32 v[248:249], v[98:99], v[40:41]
	v_pk_mul_f32 v[250:251], v[96:97], v[42:43]
	v_cvt_pk_bf16_f32 v244, v244, v245
	v_cvt_pk_bf16_f32 v245, v246, v247
	v_cvt_pk_bf16_f32 v246, v248, v249
	v_cvt_pk_bf16_f32 v247, v250, v251
	global_store_dwordx4 v208, v[244:247], s[58:59]
	v_pk_fma_f32 v[36:37], v[36:37], v[68:69], v[216:217]
	v_pk_fma_f32 v[38:39], v[38:39], v[70:71], v[218:219]
	global_store_dwordx4 v207, v[36:39], s[92:93] offset:512
	v_fmac_f32_e32 v210, v36, v36
	v_fmac_f32_e32 v210, v37, v37
	v_fmac_f32_e32 v210, v38, v38
	v_fmac_f32_e32 v210, v39, v39
	v_pk_mul_f32 v[216:217], v[86:87], v[36:37]
	v_pk_mul_f32 v[218:219], v[84:85], v[38:39]
	v_pk_fma_f32 v[32:33], v[32:33], v[64:65], v[220:221]
	v_pk_fma_f32 v[34:35], v[34:35], v[66:67], v[222:223]
	global_store_dwordx4 v207, v[32:35], s[92:93] offset:528
	v_fmac_f32_e32 v210, v32, v32
	v_fmac_f32_e32 v210, v33, v33
	v_fmac_f32_e32 v210, v34, v34
	v_fmac_f32_e32 v210, v35, v35
	v_pk_mul_f32 v[220:221], v[80:81], v[32:33]
	v_pk_mul_f32 v[222:223], v[82:83], v[34:35]
	v_cvt_pk_bf16_f32 v216, v216, v217
	v_cvt_pk_bf16_f32 v217, v218, v219
	v_cvt_pk_bf16_f32 v218, v220, v221
	v_cvt_pk_bf16_f32 v219, v222, v223
	global_store_dwordx4 v208, v[216:219], s[58:59] offset:256
	ds_bpermute_b32 v211, v203, v210
	v_add_u32_e32 v207, 0x10000, v207
	v_add_u32_e32 v206, 0x10000, v206
	global_load_dwordx4 v[248:251], v206, s[82:83] offset:16
	global_load_dwordx4 v[220:223], v206, s[82:83] offset:528
	global_load_dwordx4 v[244:247], v206, s[82:83]
	global_load_dwordx4 v[216:219], v206, s[82:83] offset:512
	s_waitcnt lgkmcnt(0)
	v_add_f32_e32 v211, v210, v211
	ds_bpermute_b32 v212, v202, v211
	v_add_u32_e32 v208, 0x8000, v208
	s_waitcnt lgkmcnt(0)
	v_add_f32_e32 v211, v211, v212
	s_mov_b64 exec, 0xffff
	global_store_dword v209, v211, s[90:91]
	s_mov_b64 exec, -1
	v_add_u32_e32 v209, 0x400, v209
	s_waitcnt vmcnt(12)
; DI u32x4 pack8(const float* v) { u32x4 w; w.x = pk2(v[0], v[1]); w.y = pk2(v[2], v[3]); w.z = pk2(v[4], v[5]); w.w = pk2(v[6], v[7]); return w; }
; #define xor16_32(s) xor16_32_l((s), fr + 16 * fq)
;     DI void operator()(AccRef acc, const Unit& u, int wr, int wc, int fr, int fq) const {
;     ...
;             for (int m = 0; m < 4; ++m) {
;                 const int row = rb + 16 * m;
;                 const float* xi = row < MP ? xin_p + (size_t)row * 1024 : xin_s + (size_t)(row - MP) * 1024;
;                 float s = 0.f;
; #pragma unroll
;                 for (int bj = 0; bj < 2; ++bj) {
;                     const int c = u.pn * 256 + bj * 128 + cl;
;                     float v[8];
; #pragma unroll
;                     for (int n = 0; n < 2; ++n) {
;                         const f32x4 x = *(const f32x4*)(xi + c + 4 * n);
;                         const f32x4 y = x + gt[bj][n] * acc[ai][bj][m][n];
;                         *(f32x4*)(xout + (size_t)row * 1024 + c + 4 * n) = y;
; #pragma unroll
;                         for (int j = 0; j < 4; ++j) { s += y[j] * y[j]; v[4 * n + j] = ap ? y[j] * gs[bj][n][j] : 0.f; }
;                     }
;                     if (ap) *(u32x4*)(ap + (size_t)row * 1024 + c) = pack8(v);
;                 }
;                 s = xor16_32(s);
;                 if (fq == 0) ssq[(size_t)row * 16 + u.pn * 4 + wc] = s;
	v_pk_fma_f32 v[28:29], v[28:29], v[76:77], v[228:229]
	v_pk_fma_f32 v[30:31], v[30:31], v[78:79], v[230:231]
	global_store_dwordx4 v207, v[28:31], s[92:93]
	v_mul_f32_e32 v210, v29, v29
	v_fmac_f32_e32 v210, v28, v28
	v_fmac_f32_e32 v210, v30, v30
	v_fmac_f32_e32 v210, v31, v31
	v_pk_mul_f32 v[228:229], v[100:101], v[28:29]
	v_pk_mul_f32 v[230:231], v[102:103], v[30:31]
	v_pk_fma_f32 v[24:25], v[24:25], v[72:73], v[232:233]
	v_pk_fma_f32 v[26:27], v[26:27], v[74:75], v[234:235]
	global_store_dwordx4 v207, v[24:27], s[92:93] offset:16
	v_fmac_f32_e32 v210, v24, v24
	v_fmac_f32_e32 v210, v25, v25
	v_fmac_f32_e32 v210, v26, v26
	v_fmac_f32_e32 v210, v27, v27
	v_pk_mul_f32 v[232:233], v[98:99], v[24:25]
	v_pk_mul_f32 v[234:235], v[96:97], v[26:27]
	v_cvt_pk_bf16_f32 v228, v228, v229
	v_cvt_pk_bf16_f32 v229, v230, v231
	v_cvt_pk_bf16_f32 v230, v232, v233
	v_cvt_pk_bf16_f32 v231, v234, v235
	global_store_dwordx4 v208, v[228:231], s[58:59]
	v_pk_fma_f32 v[20:21], v[20:21], v[68:69], v[236:237]
	v_pk_fma_f32 v[22:23], v[22:23], v[70:71], v[238:239]
	global_store_dwordx4 v207, v[20:23], s[92:93] offset:512
	v_fmac_f32_e32 v210, v20, v20
	v_fmac_f32_e32 v210, v21, v21
	v_fmac_f32_e32 v210, v22, v22
	v_fmac_f32_e32 v210, v23, v23
	v_pk_mul_f32 v[236:237], v[86:87], v[20:21]
	v_pk_mul_f32 v[238:239], v[84:85], v[22:23]
	v_pk_fma_f32 v[16:17], v[16:17], v[64:65], v[240:241]
	v_pk_fma_f32 v[18:19], v[18:19], v[66:67], v[242:243]
	global_store_dwordx4 v207, v[16:19], s[92:93] offset:528
	v_fmac_f32_e32 v210, v16, v16
	v_fmac_f32_e32 v210, v17, v17
	v_fmac_f32_e32 v210, v18, v18
	v_fmac_f32_e32 v210, v19, v19
	v_pk_mul_f32 v[240:241], v[80:81], v[16:17]
	v_pk_mul_f32 v[242:243], v[82:83], v[18:19]
	v_cvt_pk_bf16_f32 v236, v236, v237
	v_cvt_pk_bf16_f32 v237, v238, v239
	v_cvt_pk_bf16_f32 v238, v240, v241
	v_cvt_pk_bf16_f32 v239, v242, v243
	global_store_dwordx4 v208, v[236:239], s[58:59] offset:256
	ds_bpermute_b32 v211, v203, v210
	v_add_u32_e32 v207, 0x10000, v207
	s_waitcnt lgkmcnt(0)
	v_add_f32_e32 v211, v210, v211
	ds_bpermute_b32 v212, v202, v211
	v_add_u32_e32 v208, 0x8000, v208
	s_waitcnt lgkmcnt(0)
	v_add_f32_e32 v211, v211, v212
	s_mov_b64 exec, 0xffff
	global_store_dword v209, v211, s[90:91]
	s_mov_b64 exec, -1
	v_add_u32_e32 v209, 0x400, v209
	s_waitcnt vmcnt(8)
	v_pk_fma_f32 v[12:13], v[12:13], v[76:77], v[244:245]
	v_pk_fma_f32 v[14:15], v[14:15], v[78:79], v[246:247]
	global_store_dwordx4 v207, v[12:15], s[92:93]
	v_mul_f32_e32 v210, v13, v13
	v_fmac_f32_e32 v210, v12, v12
	v_fmac_f32_e32 v210, v14, v14
	v_fmac_f32_e32 v210, v15, v15
	v_pk_mul_f32 v[244:245], v[100:101], v[12:13]
	v_pk_mul_f32 v[246:247], v[102:103], v[14:15]
	v_pk_fma_f32 v[8:9], v[8:9], v[72:73], v[248:249]
	v_pk_fma_f32 v[10:11], v[10:11], v[74:75], v[250:251]
	global_store_dwordx4 v207, v[8:11], s[92:93] offset:16
	v_fmac_f32_e32 v210, v8, v8
	v_fmac_f32_e32 v210, v9, v9
	v_fmac_f32_e32 v210, v10, v10
	v_fmac_f32_e32 v210, v11, v11
	v_pk_mul_f32 v[248:249], v[98:99], v[8:9]
	v_pk_mul_f32 v[250:251], v[96:97], v[10:11]
	v_cvt_pk_bf16_f32 v244, v244, v245
	v_cvt_pk_bf16_f32 v245, v246, v247
	v_cvt_pk_bf16_f32 v246, v248, v249
	v_cvt_pk_bf16_f32 v247, v250, v251
	global_store_dwordx4 v208, v[244:247], s[58:59]
	v_pk_fma_f32 v[4:5], v[4:5], v[68:69], v[216:217]
	v_pk_fma_f32 v[6:7], v[6:7], v[70:71], v[218:219]
	global_store_dwordx4 v207, v[4:7], s[92:93] offset:512
	v_fmac_f32_e32 v210, v4, v4
	v_fmac_f32_e32 v210, v5, v5
	v_fmac_f32_e32 v210, v6, v6
	v_fmac_f32_e32 v210, v7, v7
	v_pk_mul_f32 v[216:217], v[86:87], v[4:5]
	v_pk_mul_f32 v[218:219], v[84:85], v[6:7]
	v_pk_fma_f32 v[0:1], v[0:1], v[64:65], v[220:221]
	v_pk_fma_f32 v[2:3], v[2:3], v[66:67], v[222:223]
	global_store_dwordx4 v207, v[0:3], s[92:93] offset:528
	v_fmac_f32_e32 v210, v0, v0
	v_fmac_f32_e32 v210, v1, v1
	v_fmac_f32_e32 v210, v2, v2
	v_fmac_f32_e32 v210, v3, v3
	v_pk_mul_f32 v[220:221], v[80:81], v[0:1]
	v_pk_mul_f32 v[222:223], v[82:83], v[2:3]
	v_cvt_pk_bf16_f32 v216, v216, v217
	v_cvt_pk_bf16_f32 v217, v218, v219
	v_cvt_pk_bf16_f32 v218, v220, v221
	v_cvt_pk_bf16_f32 v219, v222, v223
	global_store_dwordx4 v208, v[216:219], s[58:59] offset:256
	ds_bpermute_b32 v211, v203, v210
	s_waitcnt lgkmcnt(0)
	v_add_f32_e32 v211, v210, v211
	ds_bpermute_b32 v212, v202, v211
	s_waitcnt lgkmcnt(0)
	v_add_f32_e32 v211, v211, v212
	s_mov_b64 exec, 0xffff
	global_store_dword v209, v211, s[90:91]
	s_mov_b64 exec, -1
	s_andn2_b64 vcc, exec, s[8:9]
	s_mov_b64 s[0:1], -1
	s_cbranch_vccnz .LBB0_1292
	s_andn2_b64 vcc, exec, s[2:3]
	s_cbranch_vccnz .LBB0_1291
	s_barrier
	s_branch .LBB0_1291
